# GEMM K-loops: merged vmcnt+lgkmcnt waits, dropped duplicate lgkmcnt(0) and mid-block setprio flips
# baseline (speedup 1.0000x reference)
; #define PG8_STAGE(bufoff, gbase, voff) do { _Pragma("unroll") for (int _i = 0; _i < 2; ++_i) \
;         __builtin_amdgcn_global_load_lds((const unsigned*)((const char*)(gbase) + (voff)[_i]), (PG8_LAS unsigned*)(lds + (bufoff) + ldsw + _i * 8192), 16, 0, 0); } while (0)
; #define PG8_LDA(dst, b, h) do { _Pragma("unroll") for (int m = 0; m < 4; ++m) _Pragma("unroll") for (int k = 0; k < 2; ++k) dst[m][k] = *(const PG8_LAS bf16x8*)(lds + PG8_SA(b, h) + aoff + m * 2048 + k * 1024); } while (0)
; #define PG8_LDB(dst, b, h) do { _Pragma("unroll") for (int n = 0; n < 2; ++n) _Pragma("unroll") for (int k = 0; k < 2; ++k) dst[n][k] = *(const PG8_LAS bf16x8*)(lds + PG8_SB(b, h) + boff + n * 2048 + k * 1024); } while (0)
; #define PG8_MMA(ai, bj, At, Bt) do { __builtin_amdgcn_s_setprio(1); _Pragma("unroll") for (int m = 0; m < 4; ++m) _Pragma("unroll") for (int n = 0; n < 2; ++n) _Pragma("unroll") for (int k = 0; k < 2; ++k) \
;         acc[ai][bj][m][n] = __builtin_amdgcn_mfma_f32_16x16x32_bf16(Bt[n][k], At[m][k], acc[ai][bj][m][n], 0, 0, 0); __builtin_amdgcn_s_setprio(0); } while (0)
; #define PG8_WAIT_V(n) asm volatile("s_waitcnt vmcnt(" #n ")" ::: "memory")
; #define PG8_WAIT_L(n) asm volatile("s_waitcnt lgkmcnt(" #n ")" ::: "memory")
; #define PG8_BAR __builtin_amdgcn_s_barrier()
; #define PG8_SCHED __builtin_amdgcn_sched_barrier(0)
; template <class Epi, class Sched, bool ALIGN_EPI = false, bool SP2 = false>
; __device__ __forceinline__ void gemm_phase(PG8_LAS unsigned char* lds, const Gemm g, const Sched& S, const Epi& E, int wave_s) {
;     ...
;             PG8_LDB(B0, 0, 0); PG8_LDB(B1, 0, 1); PG8_SCHED; PG8_LDA(At, 0, 0); PG8_STAGE(PG8_SA(1, 1), a1 + hstep, voffA);
;             PG8_WAIT_V(8); PG8_WAIT_L(0); PG8_BAR; PG8_MMA(0, 0, At, B0); PG8_MMA(0, 1, At, B1); PG8_BAR; PG8_SCHED;
;             PG8_LDA(At, 0, 1); PG8_STAGE(PG8_SB(0, 0), b2, voffB); PG8_STAGE(PG8_SB(0, 1), b2 + hstep, voffB); PG8_STAGE(PG8_SA(0, 0), a2, voffA);
.LBB0_120:
	ds_read_b128 v[128:131], v187
	ds_read_b128 v[132:135], v187 offset:1024
	ds_read_b128 v[160:163], v187 offset:2048
	ds_read_b128 v[164:167], v187 offset:3072
	ds_read_b128 v[168:171], v188
	ds_read_b128 v[172:175], v188 offset:1024
	ds_read_b128 v[176:179], v188 offset:2048
	ds_read_b128 v[192:195], v188 offset:3072
	s_add_u32 s6, s4, 0xfffc0080
	s_addc_u32 s7, s5, -1
	s_cmp_eq_u32 s67, 12
	s_cselect_b32 s9, s3, s7
	s_cselect_b32 s8, s10, s6
	s_cselect_b32 s7, s11, s57
	s_cselect_b32 s6, s12, s47
	v_lshl_add_u64 v[180:181], s[4:5], 0, v[152:153]
	s_add_i32 m0, s65, 0xc000
	ds_read_b128 v[196:199], v189
	ds_read_b128 v[200:203], v189 offset:1024
	ds_read_b128 v[204:207], v189 offset:2048
	ds_read_b128 v[208:211], v189 offset:3072
	ds_read_b128 v[212:215], v189 offset:4096
	ds_read_b128 v[216:219], v189 offset:5120
	ds_read_b128 v[220:223], v189 offset:6144
	ds_read_b128 v[224:227], v189 offset:7168
	global_load_lds_dwordx4 v[180:181], off
	s_add_i32 m0, s65, 0xe000
	v_lshl_add_u64 v[180:181], s[4:5], 0, v[154:155]
	global_load_lds_dwordx4 v[180:181], off
	s_waitcnt vmcnt(8) lgkmcnt(0)
	s_barrier
	s_setprio 1
	v_mfma_f32_16x16x32_bf16 v[124:127], v[128:131], v[196:199], v[124:127]
	v_mfma_f32_16x16x32_bf16 v[120:123], v[160:163], v[196:199], v[120:123]
	v_mfma_f32_16x16x32_bf16 v[108:111], v[128:131], v[204:207], v[108:111]
	v_mfma_f32_16x16x32_bf16 v[104:107], v[160:163], v[204:207], v[104:107]
	v_mfma_f32_16x16x32_bf16 v[92:95], v[128:131], v[212:215], v[92:95]
	v_mfma_f32_16x16x32_bf16 v[88:91], v[160:163], v[212:215], v[88:91]
	v_mfma_f32_16x16x32_bf16 v[76:79], v[128:131], v[220:223], v[76:79]
	v_mfma_f32_16x16x32_bf16 v[72:75], v[160:163], v[220:223], v[72:75]
	v_mfma_f32_16x16x32_bf16 v[124:127], v[132:135], v[200:203], v[124:127]
	v_mfma_f32_16x16x32_bf16 v[120:123], v[164:167], v[200:203], v[120:123]
	v_mfma_f32_16x16x32_bf16 v[108:111], v[132:135], v[208:211], v[108:111]
	v_mfma_f32_16x16x32_bf16 v[104:107], v[164:167], v[208:211], v[104:107]
	v_mfma_f32_16x16x32_bf16 v[92:95], v[132:135], v[216:219], v[92:95]
	v_mfma_f32_16x16x32_bf16 v[88:91], v[164:167], v[216:219], v[88:91]
	v_mfma_f32_16x16x32_bf16 v[76:79], v[132:135], v[224:227], v[76:79]
	v_mfma_f32_16x16x32_bf16 v[72:75], v[164:167], v[224:227], v[72:75]
	v_mfma_f32_16x16x32_bf16 v[116:119], v[168:171], v[196:199], v[116:119]
	v_mfma_f32_16x16x32_bf16 v[112:115], v[176:179], v[196:199], v[112:115]
	v_mfma_f32_16x16x32_bf16 v[96:99], v[168:171], v[204:207], v[96:99]
	v_mfma_f32_16x16x32_bf16 v[100:103], v[176:179], v[204:207], v[100:103]
	v_mfma_f32_16x16x32_bf16 v[80:83], v[168:171], v[212:215], v[80:83]
	v_mfma_f32_16x16x32_bf16 v[84:87], v[176:179], v[212:215], v[84:87]
	v_mfma_f32_16x16x32_bf16 v[64:67], v[168:171], v[220:223], v[64:67]
	v_mfma_f32_16x16x32_bf16 v[68:71], v[176:179], v[220:223], v[68:71]
	v_mfma_f32_16x16x32_bf16 v[116:119], v[172:175], v[200:203], v[116:119]
	v_mfma_f32_16x16x32_bf16 v[112:115], v[192:195], v[200:203], v[112:115]
	v_mfma_f32_16x16x32_bf16 v[96:99], v[172:175], v[208:211], v[96:99]
	v_mfma_f32_16x16x32_bf16 v[100:103], v[192:195], v[208:211], v[100:103]
	v_mfma_f32_16x16x32_bf16 v[80:83], v[172:175], v[216:219], v[80:83]
	v_mfma_f32_16x16x32_bf16 v[84:87], v[192:195], v[216:219], v[84:87]
	v_mfma_f32_16x16x32_bf16 v[64:67], v[172:175], v[224:227], v[64:67]
	v_mfma_f32_16x16x32_bf16 v[68:71], v[192:195], v[224:227], v[68:71]
	s_setprio 0
	s_barrier
	s_add_i32 s58, s16, s59
	v_lshl_add_u64 v[180:181], s[6:7], 0, v[138:139]
	s_mov_b32 m0, s58
	ds_read_b128 v[196:199], v189 offset:16384
	ds_read_b128 v[200:203], v189 offset:17408
	ds_read_b128 v[204:207], v189 offset:18432
	ds_read_b128 v[208:211], v189 offset:19456
	ds_read_b128 v[212:215], v189 offset:20480
	ds_read_b128 v[216:219], v189 offset:21504
	ds_read_b128 v[220:223], v189 offset:22528
	ds_read_b128 v[224:227], v189 offset:23552
	global_load_lds_dwordx4 v[180:181], off
	s_add_i32 m0, s58, 0x2000
	s_add_u32 s76, s6, 0x40000
	v_lshl_add_u64 v[228:229], s[6:7], 0, v[142:143]
	s_addc_u32 s77, s7, 0
	s_add_i32 s58, s17, s59
	global_load_lds_dwordx4 v[228:229], off
	v_lshl_add_u64 v[230:231], s[76:77], 0, v[138:139]
	s_mov_b32 m0, s58
	v_lshl_add_u64 v[232:233], s[8:9], 0, v[140:141]
	global_load_lds_dwordx4 v[230:231], off
	s_add_i32 m0, s58, 0x2000
	v_lshl_add_u64 v[230:231], s[76:77], 0, v[142:143]
	global_load_lds_dwordx4 v[230:231], off
	s_mov_b32 m0, s65
	v_lshl_add_u64 v[230:231], s[8:9], 0, v[136:137]
	global_load_lds_dwordx4 v[230:231], off
	s_mov_b32 m0, s75
	s_nop 0
	global_load_lds_dwordx4 v[232:233], off
	s_waitcnt vmcnt(8) lgkmcnt(0)
	s_barrier
; #define PG8_STAGE(bufoff, gbase, voff) do { _Pragma("unroll") for (int _i = 0; _i < 2; ++_i) \
;         __builtin_amdgcn_global_load_lds((const unsigned*)((const char*)(gbase) + (voff)[_i]), (PG8_LAS unsigned*)(lds + (bufoff) + ldsw + _i * 8192), 16, 0, 0); } while (0)
; #define PG8_LDA(dst, b, h) do { _Pragma("unroll") for (int m = 0; m < 4; ++m) _Pragma("unroll") for (int k = 0; k < 2; ++k) dst[m][k] = *(const PG8_LAS bf16x8*)(lds + PG8_SA(b, h) + aoff + m * 2048 + k * 1024); } while (0)
; #define PG8_LDB(dst, b, h) do { _Pragma("unroll") for (int n = 0; n < 2; ++n) _Pragma("unroll") for (int k = 0; k < 2; ++k) dst[n][k] = *(const PG8_LAS bf16x8*)(lds + PG8_SB(b, h) + boff + n * 2048 + k * 1024); } while (0)
; #define PG8_MMA(ai, bj, At, Bt) do { __builtin_amdgcn_s_setprio(1); _Pragma("unroll") for (int m = 0; m < 4; ++m) _Pragma("unroll") for (int n = 0; n < 2; ++n) _Pragma("unroll") for (int k = 0; k < 2; ++k) \
;         acc[ai][bj][m][n] = __builtin_amdgcn_mfma_f32_16x16x32_bf16(Bt[n][k], At[m][k], acc[ai][bj][m][n], 0, 0, 0); __builtin_amdgcn_s_setprio(0); } while (0)
; #define PG8_WAIT_V(n) asm volatile("s_waitcnt vmcnt(" #n ")" ::: "memory")
; #define PG8_WAIT_L(n) asm volatile("s_waitcnt lgkmcnt(" #n ")" ::: "memory")
; #define PG8_BAR __builtin_amdgcn_s_barrier()
; #define PG8_SCHED __builtin_amdgcn_sched_barrier(0)
; template <class Epi, class Sched, bool ALIGN_EPI = false, bool SP2 = false>
; __device__ __forceinline__ void gemm_phase(PG8_LAS unsigned char* lds, const Gemm g, const Sched& S, const Epi& E, int wave_s) {
;     ...
;             PG8_WAIT_V(8); PG8_WAIT_L(0); PG8_BAR; PG8_MMA(1, 0, At, B0); PG8_MMA(1, 1, At, B1); PG8_BAR; PG8_SCHED;
;             PG8_LDB(B0, 1, 0); PG8_LDB(B1, 1, 1); PG8_SCHED; PG8_LDA(At, 1, 0); PG8_STAGE(PG8_SA(0, 1), a2 + hstep, voffA);
;             PG8_WAIT_V(8); PG8_WAIT_L(0); PG8_BAR; PG8_MMA(0, 0, At, B0); PG8_MMA(0, 1, At, B1); PG8_BAR; PG8_SCHED;
	s_setprio 1
	v_mfma_f32_16x16x32_bf16 v[60:63], v[128:131], v[196:199], v[60:63]
	v_mfma_f32_16x16x32_bf16 v[56:59], v[160:163], v[196:199], v[56:59]
	v_mfma_f32_16x16x32_bf16 v[44:47], v[128:131], v[204:207], v[44:47]
	v_mfma_f32_16x16x32_bf16 v[40:43], v[160:163], v[204:207], v[40:43]
	v_mfma_f32_16x16x32_bf16 v[28:31], v[128:131], v[212:215], v[28:31]
	v_mfma_f32_16x16x32_bf16 v[24:27], v[160:163], v[212:215], v[24:27]
	v_mfma_f32_16x16x32_bf16 v[12:15], v[128:131], v[220:223], v[12:15]
	v_mfma_f32_16x16x32_bf16 v[8:11], v[160:163], v[220:223], v[8:11]
	v_mfma_f32_16x16x32_bf16 v[60:63], v[132:135], v[200:203], v[60:63]
	v_mfma_f32_16x16x32_bf16 v[56:59], v[164:167], v[200:203], v[56:59]
	v_mfma_f32_16x16x32_bf16 v[44:47], v[132:135], v[208:211], v[44:47]
	v_mfma_f32_16x16x32_bf16 v[40:43], v[164:167], v[208:211], v[40:43]
	v_mfma_f32_16x16x32_bf16 v[28:31], v[132:135], v[216:219], v[28:31]
	v_mfma_f32_16x16x32_bf16 v[24:27], v[164:167], v[216:219], v[24:27]
	v_mfma_f32_16x16x32_bf16 v[12:15], v[132:135], v[224:227], v[12:15]
	v_mfma_f32_16x16x32_bf16 v[8:11], v[164:167], v[224:227], v[8:11]
	v_mfma_f32_16x16x32_bf16 v[48:51], v[168:171], v[196:199], v[48:51]
	v_mfma_f32_16x16x32_bf16 v[52:55], v[176:179], v[196:199], v[52:55]
	v_mfma_f32_16x16x32_bf16 v[32:35], v[168:171], v[204:207], v[32:35]
	v_mfma_f32_16x16x32_bf16 v[36:39], v[176:179], v[204:207], v[36:39]
	v_mfma_f32_16x16x32_bf16 v[16:19], v[168:171], v[212:215], v[16:19]
	v_mfma_f32_16x16x32_bf16 v[20:23], v[176:179], v[212:215], v[20:23]
	v_mfma_f32_16x16x32_bf16 v[0:3], v[168:171], v[220:223], v[0:3]
	v_mfma_f32_16x16x32_bf16 v[4:7], v[176:179], v[220:223], v[4:7]
	v_mfma_f32_16x16x32_bf16 v[48:51], v[172:175], v[200:203], v[48:51]
	v_mfma_f32_16x16x32_bf16 v[52:55], v[192:195], v[200:203], v[52:55]
	v_mfma_f32_16x16x32_bf16 v[32:35], v[172:175], v[208:211], v[32:35]
	v_mfma_f32_16x16x32_bf16 v[36:39], v[192:195], v[208:211], v[36:39]
	v_mfma_f32_16x16x32_bf16 v[16:19], v[172:175], v[216:219], v[16:19]
	v_mfma_f32_16x16x32_bf16 v[20:23], v[192:195], v[216:219], v[20:23]
	v_mfma_f32_16x16x32_bf16 v[0:3], v[172:175], v[224:227], v[0:3]
	v_mfma_f32_16x16x32_bf16 v[4:7], v[192:195], v[224:227], v[4:7]
	s_setprio 0
	s_barrier
	s_add_i32 s58, 0, 0x18000
	v_add_u32_e32 v144, s58, v184
	s_add_i32 s69, 0, 0x1c000
	ds_read_b128 v[128:131], v144
	ds_read_b128 v[132:135], v144 offset:1024
	ds_read_b128 v[160:163], v144 offset:2048
	ds_read_b128 v[164:167], v144 offset:3072
	v_add_u32_e32 v144, s69, v184
	ds_read_b128 v[168:171], v144
	ds_read_b128 v[172:175], v144 offset:1024
	ds_read_b128 v[176:179], v144 offset:2048
	ds_read_b128 v[192:195], v144 offset:3072
	s_add_u32 s8, s8, 0x40000
	s_addc_u32 s9, s9, 0
	s_mov_b32 m0, s90
	v_lshl_add_u64 v[234:235], s[8:9], 0, v[136:137]
	ds_read_b128 v[196:199], v189 offset:32768
	ds_read_b128 v[200:203], v189 offset:33792
	ds_read_b128 v[204:207], v189 offset:34816
	ds_read_b128 v[208:211], v189 offset:35840
	ds_read_b128 v[212:215], v189 offset:36864
	ds_read_b128 v[216:219], v189 offset:37888
	ds_read_b128 v[220:223], v189 offset:38912
	ds_read_b128 v[224:227], v189 offset:39936
	global_load_lds_dwordx4 v[234:235], off
	s_mov_b32 m0, s92
	v_lshl_add_u64 v[234:235], s[8:9], 0, v[140:141]
	global_load_lds_dwordx4 v[234:235], off
	s_waitcnt vmcnt(8) lgkmcnt(0)
	s_barrier
	s_setprio 1
	v_mfma_f32_16x16x32_bf16 v[124:127], v[128:131], v[196:199], v[124:127]
	v_mfma_f32_16x16x32_bf16 v[120:123], v[160:163], v[196:199], v[120:123]
	v_mfma_f32_16x16x32_bf16 v[108:111], v[128:131], v[204:207], v[108:111]
	v_mfma_f32_16x16x32_bf16 v[104:107], v[160:163], v[204:207], v[104:107]
	v_mfma_f32_16x16x32_bf16 v[92:95], v[128:131], v[212:215], v[92:95]
	v_mfma_f32_16x16x32_bf16 v[88:91], v[160:163], v[212:215], v[88:91]
	v_mfma_f32_16x16x32_bf16 v[76:79], v[128:131], v[220:223], v[76:79]
	v_mfma_f32_16x16x32_bf16 v[72:75], v[160:163], v[220:223], v[72:75]
	v_mfma_f32_16x16x32_bf16 v[124:127], v[132:135], v[200:203], v[124:127]
	v_mfma_f32_16x16x32_bf16 v[120:123], v[164:167], v[200:203], v[120:123]
	v_mfma_f32_16x16x32_bf16 v[108:111], v[132:135], v[208:211], v[108:111]
	v_mfma_f32_16x16x32_bf16 v[104:107], v[164:167], v[208:211], v[104:107]
	v_mfma_f32_16x16x32_bf16 v[92:95], v[132:135], v[216:219], v[92:95]
	v_mfma_f32_16x16x32_bf16 v[88:91], v[164:167], v[216:219], v[88:91]
	v_mfma_f32_16x16x32_bf16 v[76:79], v[132:135], v[224:227], v[76:79]
	v_mfma_f32_16x16x32_bf16 v[72:75], v[164:167], v[224:227], v[72:75]
	v_mfma_f32_16x16x32_bf16 v[116:119], v[168:171], v[196:199], v[116:119]
	v_mfma_f32_16x16x32_bf16 v[112:115], v[176:179], v[196:199], v[112:115]
	v_mfma_f32_16x16x32_bf16 v[96:99], v[168:171], v[204:207], v[96:99]
	v_mfma_f32_16x16x32_bf16 v[100:103], v[176:179], v[204:207], v[100:103]
	v_mfma_f32_16x16x32_bf16 v[80:83], v[168:171], v[212:215], v[80:83]
	v_mfma_f32_16x16x32_bf16 v[84:87], v[176:179], v[212:215], v[84:87]
	v_mfma_f32_16x16x32_bf16 v[64:67], v[168:171], v[220:223], v[64:67]
	v_mfma_f32_16x16x32_bf16 v[68:71], v[176:179], v[220:223], v[68:71]
	v_mfma_f32_16x16x32_bf16 v[116:119], v[172:175], v[200:203], v[116:119]
	v_mfma_f32_16x16x32_bf16 v[112:115], v[192:195], v[200:203], v[112:115]
	v_mfma_f32_16x16x32_bf16 v[96:99], v[172:175], v[208:211], v[96:99]
	v_mfma_f32_16x16x32_bf16 v[100:103], v[192:195], v[208:211], v[100:103]
	v_mfma_f32_16x16x32_bf16 v[80:83], v[172:175], v[216:219], v[80:83]
	v_mfma_f32_16x16x32_bf16 v[84:87], v[192:195], v[216:219], v[84:87]
	v_mfma_f32_16x16x32_bf16 v[64:67], v[172:175], v[224:227], v[64:67]
	v_mfma_f32_16x16x32_bf16 v[68:71], v[192:195], v[224:227], v[68:71]
	s_setprio 0
	s_barrier
; #define PG8_STAGE(bufoff, gbase, voff) do { _Pragma("unroll") for (int _i = 0; _i < 2; ++_i) \
;         __builtin_amdgcn_global_load_lds((const unsigned*)((const char*)(gbase) + (voff)[_i]), (PG8_LAS unsigned*)(lds + (bufoff) + ldsw + _i * 8192), 16, 0, 0); } while (0)
; #define PG8_LDA(dst, b, h) do { _Pragma("unroll") for (int m = 0; m < 4; ++m) _Pragma("unroll") for (int k = 0; k < 2; ++k) dst[m][k] = *(const PG8_LAS bf16x8*)(lds + PG8_SA(b, h) + aoff + m * 2048 + k * 1024); } while (0)
; #define PG8_MMA(ai, bj, At, Bt) do { __builtin_amdgcn_s_setprio(1); _Pragma("unroll") for (int m = 0; m < 4; ++m) _Pragma("unroll") for (int n = 0; n < 2; ++n) _Pragma("unroll") for (int k = 0; k < 2; ++k) \
;         acc[ai][bj][m][n] = __builtin_amdgcn_mfma_f32_16x16x32_bf16(Bt[n][k], At[m][k], acc[ai][bj][m][n], 0, 0, 0); __builtin_amdgcn_s_setprio(0); } while (0)
; #define PG8_WAIT_V(n) asm volatile("s_waitcnt vmcnt(" #n ")" ::: "memory")
; #define PG8_WAIT_L(n) asm volatile("s_waitcnt lgkmcnt(" #n ")" ::: "memory")
; #define PG8_BAR __builtin_amdgcn_s_barrier()
; #define PG8_SCHED __builtin_amdgcn_sched_barrier(0)
; template <class Epi, class Sched, bool ALIGN_EPI = false, bool SP2 = false>
; __device__ __forceinline__ void gemm_phase(PG8_LAS unsigned char* lds, const Gemm g, const Sched& S, const Epi& E, int wave_s) {
;     ...
;         for (int t = 0; t < nt; t += 2) {
;             const bool last = (t == nt - 2);
;     ...
;             PG8_LDA(At, 1, 1); PG8_STAGE(PG8_SB(1, 0), b3, voffB); PG8_STAGE(PG8_SB(1, 1), b3 + hstep, voffB); PG8_STAGE(PG8_SA(1, 0), a3, voffA);
;             PG8_WAIT_V(8); PG8_WAIT_L(0); PG8_BAR; PG8_MMA(1, 0, At, B0); PG8_MMA(1, 1, At, B1); PG8_BAR; PG8_SCHED;
;     ...
;         if constexpr (ALIGN_EPI) { if (wr == 0) PG8_BAR; }
	s_add_i32 s8, s58, s59
	v_lshl_add_u64 v[180:181], v[180:181], 0, s[30:31]
	s_mov_b32 m0, s8
	ds_read_b128 v[196:199], v189 offset:49152
	ds_read_b128 v[200:203], v189 offset:50176
	ds_read_b128 v[204:207], v189 offset:51200
	ds_read_b128 v[208:211], v189 offset:52224
	ds_read_b128 v[212:215], v189 offset:53248
	ds_read_b128 v[216:219], v189 offset:54272
	ds_read_b128 v[220:223], v189 offset:55296
	ds_read_b128 v[224:227], v189 offset:56320
	global_load_lds_dwordx4 v[180:181], off
	s_add_i32 m0, s8, 0x2000
	s_add_u32 s6, s6, 0x40080
	v_lshl_add_u64 v[180:181], v[228:229], 0, s[30:31]
	s_addc_u32 s7, s7, 0
	s_add_i32 s8, s69, s59
	global_load_lds_dwordx4 v[180:181], off
	s_mov_b32 m0, s8
	v_lshl_add_u64 v[180:181], s[6:7], 0, v[138:139]
	global_load_lds_dwordx4 v[180:181], off
	s_add_i32 m0, s8, 0x2000
	v_lshl_add_u64 v[180:181], s[6:7], 0, v[142:143]
	global_load_lds_dwordx4 v[180:181], off
	s_mov_b32 m0, s94
	v_lshl_add_u64 v[180:181], v[230:231], 0, s[30:31]
	global_load_lds_dwordx4 v[180:181], off
	s_mov_b32 m0, s95
	v_lshl_add_u64 v[180:181], v[232:233], 0, s[30:31]
	global_load_lds_dwordx4 v[180:181], off
	s_waitcnt vmcnt(8) lgkmcnt(0)
	s_barrier
	s_setprio 1
	v_mfma_f32_16x16x32_bf16 v[60:63], v[128:131], v[196:199], v[60:63]
	v_mfma_f32_16x16x32_bf16 v[56:59], v[160:163], v[196:199], v[56:59]
	v_mfma_f32_16x16x32_bf16 v[44:47], v[128:131], v[204:207], v[44:47]
	v_mfma_f32_16x16x32_bf16 v[40:43], v[160:163], v[204:207], v[40:43]
	v_mfma_f32_16x16x32_bf16 v[28:31], v[128:131], v[212:215], v[28:31]
	v_mfma_f32_16x16x32_bf16 v[24:27], v[160:163], v[212:215], v[24:27]
	v_mfma_f32_16x16x32_bf16 v[12:15], v[128:131], v[220:223], v[12:15]
	v_mfma_f32_16x16x32_bf16 v[8:11], v[160:163], v[220:223], v[8:11]
	v_mfma_f32_16x16x32_bf16 v[60:63], v[132:135], v[200:203], v[60:63]
	v_mfma_f32_16x16x32_bf16 v[56:59], v[164:167], v[200:203], v[56:59]
	v_mfma_f32_16x16x32_bf16 v[44:47], v[132:135], v[208:211], v[44:47]
	v_mfma_f32_16x16x32_bf16 v[40:43], v[164:167], v[208:211], v[40:43]
	v_mfma_f32_16x16x32_bf16 v[28:31], v[132:135], v[216:219], v[28:31]
	v_mfma_f32_16x16x32_bf16 v[24:27], v[164:167], v[216:219], v[24:27]
	v_mfma_f32_16x16x32_bf16 v[12:15], v[132:135], v[224:227], v[12:15]
	v_mfma_f32_16x16x32_bf16 v[8:11], v[164:167], v[224:227], v[8:11]
	v_mfma_f32_16x16x32_bf16 v[48:51], v[168:171], v[196:199], v[48:51]
	v_mfma_f32_16x16x32_bf16 v[52:55], v[176:179], v[196:199], v[52:55]
	v_mfma_f32_16x16x32_bf16 v[32:35], v[168:171], v[204:207], v[32:35]
	v_mfma_f32_16x16x32_bf16 v[36:39], v[176:179], v[204:207], v[36:39]
	v_mfma_f32_16x16x32_bf16 v[16:19], v[168:171], v[212:215], v[16:19]
	v_mfma_f32_16x16x32_bf16 v[20:23], v[176:179], v[212:215], v[20:23]
	v_mfma_f32_16x16x32_bf16 v[0:3], v[168:171], v[220:223], v[0:3]
	v_mfma_f32_16x16x32_bf16 v[4:7], v[176:179], v[220:223], v[4:7]
	v_mfma_f32_16x16x32_bf16 v[48:51], v[172:175], v[200:203], v[48:51]
	v_mfma_f32_16x16x32_bf16 v[52:55], v[192:195], v[200:203], v[52:55]
	v_mfma_f32_16x16x32_bf16 v[32:35], v[172:175], v[208:211], v[32:35]
	v_mfma_f32_16x16x32_bf16 v[36:39], v[192:195], v[208:211], v[36:39]
	v_mfma_f32_16x16x32_bf16 v[16:19], v[172:175], v[216:219], v[16:19]
	v_mfma_f32_16x16x32_bf16 v[20:23], v[192:195], v[216:219], v[20:23]
	v_mfma_f32_16x16x32_bf16 v[0:3], v[172:175], v[224:227], v[0:3]
	v_mfma_f32_16x16x32_bf16 v[4:7], v[192:195], v[224:227], v[4:7]
	s_setprio 0
	s_barrier
	s_add_i32 s67, s67, 2
	s_add_u32 s4, s4, 0x100
	s_addc_u32 s5, s5, 0
	s_add_u32 s47, s47, 0x100
	s_addc_u32 s57, s57, 0
	s_cmp_gt_u32 s67, 13
	s_cbranch_scc0 .LBB0_120
	s_and_b64 vcc, exec, s[78:79]
	s_cbranch_vccz .LBB0_123
	s_barrier

; #define PG8_STAGE(bufoff, gbase, voff) do { _Pragma("unroll") for (int _i = 0; _i < 2; ++_i) \
;         __builtin_amdgcn_global_load_lds((const unsigned*)((const char*)(gbase) + (voff)[_i]), (PG8_LAS unsigned*)(lds + (bufoff) + ldsw + _i * 8192), 16, 0, 0); } while (0)
; #define PG8_LDA(dst, b, h) do { _Pragma("unroll") for (int m = 0; m < 4; ++m) _Pragma("unroll") for (int k = 0; k < 2; ++k) dst[m][k] = *(const PG8_LAS bf16x8*)(lds + PG8_SA(b, h) + aoff + m * 2048 + k * 1024); } while (0)
; #define PG8_LDB(dst, b, h) do { _Pragma("unroll") for (int n = 0; n < 2; ++n) _Pragma("unroll") for (int k = 0; k < 2; ++k) dst[n][k] = *(const PG8_LAS bf16x8*)(lds + PG8_SB(b, h) + boff + n * 2048 + k * 1024); } while (0)
; #define PG8_MMA(ai, bj, At, Bt) do { __builtin_amdgcn_s_setprio(1); _Pragma("unroll") for (int m = 0; m < 4; ++m) _Pragma("unroll") for (int n = 0; n < 2; ++n) _Pragma("unroll") for (int k = 0; k < 2; ++k) \
;         acc[ai][bj][m][n] = __builtin_amdgcn_mfma_f32_16x16x32_bf16(Bt[n][k], At[m][k], acc[ai][bj][m][n], 0, 0, 0); __builtin_amdgcn_s_setprio(0); } while (0)
; #define PG8_WAIT_V(n) asm volatile("s_waitcnt vmcnt(" #n ")" ::: "memory")
; #define PG8_WAIT_L(n) asm volatile("s_waitcnt lgkmcnt(" #n ")" ::: "memory")
; #define PG8_BAR __builtin_amdgcn_s_barrier()
; #define PG8_SCHED __builtin_amdgcn_sched_barrier(0)
; template <class Epi, class Sched, bool ALIGN_EPI = false, bool SP2 = false>
; __device__ __forceinline__ void gemm_phase(PG8_LAS unsigned char* lds, const Gemm g, const Sched& S, const Epi& E, int wave_s) {
;     ...
;             PG8_LDB(B0, 0, 0); PG8_LDB(B1, 0, 1); PG8_SCHED; PG8_LDA(At, 0, 0); PG8_STAGE(PG8_SA(1, 1), a1 + hstep, voffA);
;             PG8_WAIT_V(8); PG8_WAIT_L(0); PG8_BAR; PG8_MMA(0, 0, At, B0); PG8_MMA(0, 1, At, B1); PG8_BAR; PG8_SCHED;
;             PG8_LDA(At, 0, 1); PG8_STAGE(PG8_SB(0, 0), b2, voffB); PG8_STAGE(PG8_SB(0, 1), b2 + hstep, voffB); PG8_STAGE(PG8_SA(0, 0), a2, voffA);
.LBB0_1026:
	ds_read_b128 v[146:149], v153
	ds_read_b128 v[158:161], v153 offset:1024
	ds_read_b128 v[162:165], v153 offset:2048
	ds_read_b128 v[166:169], v153 offset:3072
	ds_read_b128 v[170:173], v154
	ds_read_b128 v[174:177], v154 offset:1024
	ds_read_b128 v[178:181], v154 offset:2048
	ds_read_b128 v[182:185], v154 offset:3072
	s_add_u32 s40, s26, 0xfffc0080
	s_addc_u32 s41, s27, -1
	s_cmp_eq_u32 s73, 12
	s_cselect_b32 s43, s19, s41
	s_cselect_b32 s42, s69, s40
	s_cselect_b32 s41, s17, s72
	s_cselect_b32 s40, s70, s71
	v_lshl_add_u64 v[210:211], s[26:27], 0, v[138:139]
	s_add_i32 m0, s25, 0xc000
	ds_read_b128 v[186:189], v155
	ds_read_b128 v[190:193], v155 offset:1024
	ds_read_b128 v[194:197], v155 offset:2048
	ds_read_b128 v[198:201], v155 offset:3072
	ds_read_b128 v[202:205], v155 offset:4096
	ds_read_b128 v[206:209], v155 offset:5120
	ds_read_b128 v[214:217], v155 offset:6144
	ds_read_b128 v[218:221], v155 offset:7168
	global_load_lds_dwordx4 v[210:211], off
	s_add_i32 m0, s25, 0xe000
	v_lshl_add_u64 v[210:211], s[26:27], 0, v[140:141]
	global_load_lds_dwordx4 v[210:211], off
	s_waitcnt vmcnt(8) lgkmcnt(0)
	s_barrier
	s_setprio 1
	v_mfma_f32_16x16x32_bf16 v[124:127], v[146:149], v[186:189], v[124:127]
	v_mfma_f32_16x16x32_bf16 v[120:123], v[162:165], v[186:189], v[120:123]
	v_mfma_f32_16x16x32_bf16 v[108:111], v[146:149], v[194:197], v[108:111]
	v_mfma_f32_16x16x32_bf16 v[104:107], v[162:165], v[194:197], v[104:107]
	v_mfma_f32_16x16x32_bf16 v[92:95], v[146:149], v[202:205], v[92:95]
	v_mfma_f32_16x16x32_bf16 v[88:91], v[162:165], v[202:205], v[88:91]
	v_mfma_f32_16x16x32_bf16 v[76:79], v[146:149], v[214:217], v[76:79]
	v_mfma_f32_16x16x32_bf16 v[72:75], v[162:165], v[214:217], v[72:75]
	v_mfma_f32_16x16x32_bf16 v[124:127], v[158:161], v[190:193], v[124:127]
	v_mfma_f32_16x16x32_bf16 v[120:123], v[166:169], v[190:193], v[120:123]
	v_mfma_f32_16x16x32_bf16 v[108:111], v[158:161], v[198:201], v[108:111]
	v_mfma_f32_16x16x32_bf16 v[104:107], v[166:169], v[198:201], v[104:107]
	v_mfma_f32_16x16x32_bf16 v[92:95], v[158:161], v[206:209], v[92:95]
	v_mfma_f32_16x16x32_bf16 v[88:91], v[166:169], v[206:209], v[88:91]
	v_mfma_f32_16x16x32_bf16 v[76:79], v[158:161], v[218:221], v[76:79]
	v_mfma_f32_16x16x32_bf16 v[72:75], v[166:169], v[218:221], v[72:75]
	v_mfma_f32_16x16x32_bf16 v[116:119], v[170:173], v[186:189], v[116:119]
	v_mfma_f32_16x16x32_bf16 v[112:115], v[178:181], v[186:189], v[112:115]
	v_mfma_f32_16x16x32_bf16 v[100:103], v[170:173], v[194:197], v[100:103]
	v_mfma_f32_16x16x32_bf16 v[96:99], v[178:181], v[194:197], v[96:99]
	v_mfma_f32_16x16x32_bf16 v[84:87], v[170:173], v[202:205], v[84:87]
	v_mfma_f32_16x16x32_bf16 v[80:83], v[178:181], v[202:205], v[80:83]
	v_mfma_f32_16x16x32_bf16 v[68:71], v[170:173], v[214:217], v[68:71]
	v_mfma_f32_16x16x32_bf16 v[64:67], v[178:181], v[214:217], v[64:67]
	v_mfma_f32_16x16x32_bf16 v[116:119], v[174:177], v[190:193], v[116:119]
	v_mfma_f32_16x16x32_bf16 v[112:115], v[182:185], v[190:193], v[112:115]
	v_mfma_f32_16x16x32_bf16 v[100:103], v[174:177], v[198:201], v[100:103]
	v_mfma_f32_16x16x32_bf16 v[96:99], v[182:185], v[198:201], v[96:99]
	v_mfma_f32_16x16x32_bf16 v[84:87], v[174:177], v[206:209], v[84:87]
	v_mfma_f32_16x16x32_bf16 v[80:83], v[182:185], v[206:209], v[80:83]
	v_mfma_f32_16x16x32_bf16 v[68:71], v[174:177], v[218:221], v[68:71]
	v_mfma_f32_16x16x32_bf16 v[64:67], v[182:185], v[218:221], v[64:67]
	s_setprio 0
	s_barrier
	s_add_i32 s74, s62, s49
	v_lshl_add_u64 v[210:211], s[40:41], 0, v[130:131]
	s_mov_b32 m0, s74
	ds_read_b128 v[186:189], v155 offset:16384
	ds_read_b128 v[190:193], v155 offset:17408
	ds_read_b128 v[194:197], v155 offset:18432
	ds_read_b128 v[198:201], v155 offset:19456
	ds_read_b128 v[202:205], v155 offset:20480
	ds_read_b128 v[206:209], v155 offset:21504
	ds_read_b128 v[214:217], v155 offset:22528
	ds_read_b128 v[218:221], v155 offset:23552
	global_load_lds_dwordx4 v[210:211], off
	s_add_i32 m0, s74, 0x2000
	s_add_u32 s74, s40, 0x40000
	v_lshl_add_u64 v[222:223], s[40:41], 0, v[134:135]
	s_addc_u32 s75, s41, 0
	s_add_i32 s76, s63, s49
	global_load_lds_dwordx4 v[222:223], off
	v_lshl_add_u64 v[224:225], s[74:75], 0, v[130:131]
	s_mov_b32 m0, s76
	v_lshl_add_u64 v[226:227], s[42:43], 0, v[132:133]
	global_load_lds_dwordx4 v[224:225], off
	s_add_i32 m0, s76, 0x2000
	v_lshl_add_u64 v[224:225], s[74:75], 0, v[134:135]
	global_load_lds_dwordx4 v[224:225], off
	s_mov_b32 m0, s25
	v_lshl_add_u64 v[224:225], s[42:43], 0, v[128:129]
	global_load_lds_dwordx4 v[224:225], off
	s_mov_b32 m0, s50
	s_nop 0
	global_load_lds_dwordx4 v[226:227], off
	s_waitcnt vmcnt(8) lgkmcnt(0)
	s_barrier
; #define PG8_STAGE(bufoff, gbase, voff) do { _Pragma("unroll") for (int _i = 0; _i < 2; ++_i) \
;         __builtin_amdgcn_global_load_lds((const unsigned*)((const char*)(gbase) + (voff)[_i]), (PG8_LAS unsigned*)(lds + (bufoff) + ldsw + _i * 8192), 16, 0, 0); } while (0)
; #define PG8_LDA(dst, b, h) do { _Pragma("unroll") for (int m = 0; m < 4; ++m) _Pragma("unroll") for (int k = 0; k < 2; ++k) dst[m][k] = *(const PG8_LAS bf16x8*)(lds + PG8_SA(b, h) + aoff + m * 2048 + k * 1024); } while (0)
; #define PG8_LDB(dst, b, h) do { _Pragma("unroll") for (int n = 0; n < 2; ++n) _Pragma("unroll") for (int k = 0; k < 2; ++k) dst[n][k] = *(const PG8_LAS bf16x8*)(lds + PG8_SB(b, h) + boff + n * 2048 + k * 1024); } while (0)
; #define PG8_MMA(ai, bj, At, Bt) do { __builtin_amdgcn_s_setprio(1); _Pragma("unroll") for (int m = 0; m < 4; ++m) _Pragma("unroll") for (int n = 0; n < 2; ++n) _Pragma("unroll") for (int k = 0; k < 2; ++k) \
;         acc[ai][bj][m][n] = __builtin_amdgcn_mfma_f32_16x16x32_bf16(Bt[n][k], At[m][k], acc[ai][bj][m][n], 0, 0, 0); __builtin_amdgcn_s_setprio(0); } while (0)
; #define PG8_WAIT_V(n) asm volatile("s_waitcnt vmcnt(" #n ")" ::: "memory")
; #define PG8_WAIT_L(n) asm volatile("s_waitcnt lgkmcnt(" #n ")" ::: "memory")
; #define PG8_BAR __builtin_amdgcn_s_barrier()
; #define PG8_SCHED __builtin_amdgcn_sched_barrier(0)
; template <class Epi, class Sched, bool ALIGN_EPI = false, bool SP2 = false>
; __device__ __forceinline__ void gemm_phase(PG8_LAS unsigned char* lds, const Gemm g, const Sched& S, const Epi& E, int wave_s) {
;     ...
;             PG8_WAIT_V(8); PG8_WAIT_L(0); PG8_BAR; PG8_MMA(1, 0, At, B0); PG8_MMA(1, 1, At, B1); PG8_BAR; PG8_SCHED;
;             PG8_LDB(B0, 1, 0); PG8_LDB(B1, 1, 1); PG8_SCHED; PG8_LDA(At, 1, 0); PG8_STAGE(PG8_SA(0, 1), a2 + hstep, voffA);
;             PG8_WAIT_V(8); PG8_WAIT_L(0); PG8_BAR; PG8_MMA(0, 0, At, B0); PG8_MMA(0, 1, At, B1); PG8_BAR; PG8_SCHED;
	s_setprio 1
	v_mfma_f32_16x16x32_bf16 v[60:63], v[146:149], v[186:189], v[60:63]
	v_mfma_f32_16x16x32_bf16 v[56:59], v[162:165], v[186:189], v[56:59]
	v_mfma_f32_16x16x32_bf16 v[44:47], v[146:149], v[194:197], v[44:47]
	v_mfma_f32_16x16x32_bf16 v[40:43], v[162:165], v[194:197], v[40:43]
	v_mfma_f32_16x16x32_bf16 v[28:31], v[146:149], v[202:205], v[28:31]
	v_mfma_f32_16x16x32_bf16 v[24:27], v[162:165], v[202:205], v[24:27]
	v_mfma_f32_16x16x32_bf16 v[12:15], v[146:149], v[214:217], v[12:15]
	v_mfma_f32_16x16x32_bf16 v[8:11], v[162:165], v[214:217], v[8:11]
	v_mfma_f32_16x16x32_bf16 v[60:63], v[158:161], v[190:193], v[60:63]
	v_mfma_f32_16x16x32_bf16 v[56:59], v[166:169], v[190:193], v[56:59]
	v_mfma_f32_16x16x32_bf16 v[44:47], v[158:161], v[198:201], v[44:47]
	v_mfma_f32_16x16x32_bf16 v[40:43], v[166:169], v[198:201], v[40:43]
	v_mfma_f32_16x16x32_bf16 v[28:31], v[158:161], v[206:209], v[28:31]
	v_mfma_f32_16x16x32_bf16 v[24:27], v[166:169], v[206:209], v[24:27]
	v_mfma_f32_16x16x32_bf16 v[12:15], v[158:161], v[218:221], v[12:15]
	v_mfma_f32_16x16x32_bf16 v[8:11], v[166:169], v[218:221], v[8:11]
	v_mfma_f32_16x16x32_bf16 v[52:55], v[170:173], v[186:189], v[52:55]
	v_mfma_f32_16x16x32_bf16 v[48:51], v[178:181], v[186:189], v[48:51]
	v_mfma_f32_16x16x32_bf16 v[36:39], v[170:173], v[194:197], v[36:39]
	v_mfma_f32_16x16x32_bf16 v[32:35], v[178:181], v[194:197], v[32:35]
	v_mfma_f32_16x16x32_bf16 v[20:23], v[170:173], v[202:205], v[20:23]
	v_mfma_f32_16x16x32_bf16 v[16:19], v[178:181], v[202:205], v[16:19]
	v_mfma_f32_16x16x32_bf16 v[4:7], v[170:173], v[214:217], v[4:7]
	v_mfma_f32_16x16x32_bf16 v[0:3], v[178:181], v[214:217], v[0:3]
	v_mfma_f32_16x16x32_bf16 v[52:55], v[174:177], v[190:193], v[52:55]
	v_mfma_f32_16x16x32_bf16 v[48:51], v[182:185], v[190:193], v[48:51]
	v_mfma_f32_16x16x32_bf16 v[36:39], v[174:177], v[198:201], v[36:39]
	v_mfma_f32_16x16x32_bf16 v[32:35], v[182:185], v[198:201], v[32:35]
	v_mfma_f32_16x16x32_bf16 v[20:23], v[174:177], v[206:209], v[20:23]
	v_mfma_f32_16x16x32_bf16 v[16:19], v[182:185], v[206:209], v[16:19]
	v_mfma_f32_16x16x32_bf16 v[4:7], v[174:177], v[218:221], v[4:7]
	v_mfma_f32_16x16x32_bf16 v[0:3], v[182:185], v[218:221], v[0:3]
	s_setprio 0
	s_barrier
	s_add_i32 s74, 0, 0x18000
	v_add_u32_e32 v136, s74, v151
	s_add_i32 s75, 0, 0x1c000
	ds_read_b128 v[146:149], v136
	ds_read_b128 v[158:161], v136 offset:1024
	ds_read_b128 v[162:165], v136 offset:2048
	ds_read_b128 v[166:169], v136 offset:3072
	v_add_u32_e32 v136, s75, v151
	ds_read_b128 v[170:173], v136
	ds_read_b128 v[174:177], v136 offset:1024
	ds_read_b128 v[178:181], v136 offset:2048
	ds_read_b128 v[182:185], v136 offset:3072
	s_add_u32 s42, s42, 0x40000
	s_addc_u32 s43, s43, 0
	s_mov_b32 m0, s51
	v_lshl_add_u64 v[228:229], s[42:43], 0, v[128:129]
	ds_read_b128 v[186:189], v155 offset:32768
	ds_read_b128 v[190:193], v155 offset:33792
	ds_read_b128 v[194:197], v155 offset:34816
	ds_read_b128 v[198:201], v155 offset:35840
	ds_read_b128 v[202:205], v155 offset:36864
	ds_read_b128 v[206:209], v155 offset:37888
	ds_read_b128 v[214:217], v155 offset:38912
	ds_read_b128 v[218:221], v155 offset:39936
	global_load_lds_dwordx4 v[228:229], off
	s_mov_b32 m0, s56
	v_lshl_add_u64 v[228:229], s[42:43], 0, v[132:133]
	global_load_lds_dwordx4 v[228:229], off
	s_waitcnt vmcnt(8) lgkmcnt(0)
	s_barrier
	s_setprio 1
	v_mfma_f32_16x16x32_bf16 v[124:127], v[146:149], v[186:189], v[124:127]
	v_mfma_f32_16x16x32_bf16 v[120:123], v[162:165], v[186:189], v[120:123]
	v_mfma_f32_16x16x32_bf16 v[108:111], v[146:149], v[194:197], v[108:111]
	v_mfma_f32_16x16x32_bf16 v[104:107], v[162:165], v[194:197], v[104:107]
	v_mfma_f32_16x16x32_bf16 v[92:95], v[146:149], v[202:205], v[92:95]
	v_mfma_f32_16x16x32_bf16 v[88:91], v[162:165], v[202:205], v[88:91]
	v_mfma_f32_16x16x32_bf16 v[76:79], v[146:149], v[214:217], v[76:79]
	v_mfma_f32_16x16x32_bf16 v[72:75], v[162:165], v[214:217], v[72:75]
	v_mfma_f32_16x16x32_bf16 v[124:127], v[158:161], v[190:193], v[124:127]
	v_mfma_f32_16x16x32_bf16 v[120:123], v[166:169], v[190:193], v[120:123]
	v_mfma_f32_16x16x32_bf16 v[108:111], v[158:161], v[198:201], v[108:111]
	v_mfma_f32_16x16x32_bf16 v[104:107], v[166:169], v[198:201], v[104:107]
	v_mfma_f32_16x16x32_bf16 v[92:95], v[158:161], v[206:209], v[92:95]
	v_mfma_f32_16x16x32_bf16 v[88:91], v[166:169], v[206:209], v[88:91]
	v_mfma_f32_16x16x32_bf16 v[76:79], v[158:161], v[218:221], v[76:79]
	v_mfma_f32_16x16x32_bf16 v[72:75], v[166:169], v[218:221], v[72:75]
	v_mfma_f32_16x16x32_bf16 v[116:119], v[170:173], v[186:189], v[116:119]
	v_mfma_f32_16x16x32_bf16 v[112:115], v[178:181], v[186:189], v[112:115]
	v_mfma_f32_16x16x32_bf16 v[100:103], v[170:173], v[194:197], v[100:103]
	v_mfma_f32_16x16x32_bf16 v[96:99], v[178:181], v[194:197], v[96:99]
	v_mfma_f32_16x16x32_bf16 v[84:87], v[170:173], v[202:205], v[84:87]
	v_mfma_f32_16x16x32_bf16 v[80:83], v[178:181], v[202:205], v[80:83]
	v_mfma_f32_16x16x32_bf16 v[68:71], v[170:173], v[214:217], v[68:71]
	v_mfma_f32_16x16x32_bf16 v[64:67], v[178:181], v[214:217], v[64:67]
	v_mfma_f32_16x16x32_bf16 v[116:119], v[174:177], v[190:193], v[116:119]
	v_mfma_f32_16x16x32_bf16 v[112:115], v[182:185], v[190:193], v[112:115]
	v_mfma_f32_16x16x32_bf16 v[100:103], v[174:177], v[198:201], v[100:103]
	v_mfma_f32_16x16x32_bf16 v[96:99], v[182:185], v[198:201], v[96:99]
	v_mfma_f32_16x16x32_bf16 v[84:87], v[174:177], v[206:209], v[84:87]
	v_mfma_f32_16x16x32_bf16 v[80:83], v[182:185], v[206:209], v[80:83]
	v_mfma_f32_16x16x32_bf16 v[68:71], v[174:177], v[218:221], v[68:71]
	v_mfma_f32_16x16x32_bf16 v[64:67], v[182:185], v[218:221], v[64:67]
	s_setprio 0
	s_barrier
; #define PG8_STAGE(bufoff, gbase, voff) do { _Pragma("unroll") for (int _i = 0; _i < 2; ++_i) \
;         __builtin_amdgcn_global_load_lds((const unsigned*)((const char*)(gbase) + (voff)[_i]), (PG8_LAS unsigned*)(lds + (bufoff) + ldsw + _i * 8192), 16, 0, 0); } while (0)
; #define PG8_LDA(dst, b, h) do { _Pragma("unroll") for (int m = 0; m < 4; ++m) _Pragma("unroll") for (int k = 0; k < 2; ++k) dst[m][k] = *(const PG8_LAS bf16x8*)(lds + PG8_SA(b, h) + aoff + m * 2048 + k * 1024); } while (0)
; #define PG8_MMA(ai, bj, At, Bt) do { __builtin_amdgcn_s_setprio(1); _Pragma("unroll") for (int m = 0; m < 4; ++m) _Pragma("unroll") for (int n = 0; n < 2; ++n) _Pragma("unroll") for (int k = 0; k < 2; ++k) \
;         acc[ai][bj][m][n] = __builtin_amdgcn_mfma_f32_16x16x32_bf16(Bt[n][k], At[m][k], acc[ai][bj][m][n], 0, 0, 0); __builtin_amdgcn_s_setprio(0); } while (0)
; #define PG8_WAIT_V(n) asm volatile("s_waitcnt vmcnt(" #n ")" ::: "memory")
; #define PG8_WAIT_L(n) asm volatile("s_waitcnt lgkmcnt(" #n ")" ::: "memory")
; #define PG8_BAR __builtin_amdgcn_s_barrier()
; #define PG8_SCHED __builtin_amdgcn_sched_barrier(0)
; template <class Epi, class Sched, bool ALIGN_EPI = false, bool SP2 = false>
; __device__ __forceinline__ void gemm_phase(PG8_LAS unsigned char* lds, const Gemm g, const Sched& S, const Epi& E, int wave_s) {
;     ...
;         for (int t = 0; t < nt; t += 2) {
;             const bool last = (t == nt - 2);
;     ...
;             PG8_LDA(At, 1, 1); PG8_STAGE(PG8_SB(1, 0), b3, voffB); PG8_STAGE(PG8_SB(1, 1), b3 + hstep, voffB); PG8_STAGE(PG8_SA(1, 0), a3, voffA);
;             PG8_WAIT_V(8); PG8_WAIT_L(0); PG8_BAR; PG8_MMA(1, 0, At, B0); PG8_MMA(1, 1, At, B1); PG8_BAR; PG8_SCHED;
;     ...
;         if constexpr (ALIGN_EPI) { if (wr == 0) PG8_BAR; }
	s_add_i32 s42, s74, s49
	v_lshl_add_u64 v[210:211], v[210:211], 0, s[10:11]
	s_mov_b32 m0, s42
	ds_read_b128 v[186:189], v155 offset:49152
	ds_read_b128 v[190:193], v155 offset:50176
	ds_read_b128 v[194:197], v155 offset:51200
	ds_read_b128 v[198:201], v155 offset:52224
	ds_read_b128 v[202:205], v155 offset:53248
	ds_read_b128 v[206:209], v155 offset:54272
	ds_read_b128 v[214:217], v155 offset:55296
	ds_read_b128 v[218:221], v155 offset:56320
	global_load_lds_dwordx4 v[210:211], off
	s_add_i32 m0, s42, 0x2000
	s_add_u32 s40, s40, 0x40080
	v_lshl_add_u64 v[210:211], v[222:223], 0, s[10:11]
	s_addc_u32 s41, s41, 0
	s_add_i32 s42, s75, s49
	global_load_lds_dwordx4 v[210:211], off
	s_mov_b32 m0, s42
	v_lshl_add_u64 v[210:211], s[40:41], 0, v[130:131]
	global_load_lds_dwordx4 v[210:211], off
	s_add_i32 m0, s42, 0x2000
	v_lshl_add_u64 v[210:211], s[40:41], 0, v[134:135]
	global_load_lds_dwordx4 v[210:211], off
	s_mov_b32 m0, s58
	v_lshl_add_u64 v[210:211], v[224:225], 0, s[10:11]
	global_load_lds_dwordx4 v[210:211], off
	s_mov_b32 m0, s59
	v_lshl_add_u64 v[210:211], v[226:227], 0, s[10:11]
	global_load_lds_dwordx4 v[210:211], off
	s_waitcnt vmcnt(8) lgkmcnt(0)
	s_barrier
	s_setprio 1
	v_mfma_f32_16x16x32_bf16 v[60:63], v[146:149], v[186:189], v[60:63]
	v_mfma_f32_16x16x32_bf16 v[56:59], v[162:165], v[186:189], v[56:59]
	v_mfma_f32_16x16x32_bf16 v[44:47], v[146:149], v[194:197], v[44:47]
	v_mfma_f32_16x16x32_bf16 v[40:43], v[162:165], v[194:197], v[40:43]
	v_mfma_f32_16x16x32_bf16 v[28:31], v[146:149], v[202:205], v[28:31]
	v_mfma_f32_16x16x32_bf16 v[24:27], v[162:165], v[202:205], v[24:27]
	v_mfma_f32_16x16x32_bf16 v[12:15], v[146:149], v[214:217], v[12:15]
	v_mfma_f32_16x16x32_bf16 v[8:11], v[162:165], v[214:217], v[8:11]
	v_mfma_f32_16x16x32_bf16 v[60:63], v[158:161], v[190:193], v[60:63]
	v_mfma_f32_16x16x32_bf16 v[56:59], v[166:169], v[190:193], v[56:59]
	v_mfma_f32_16x16x32_bf16 v[44:47], v[158:161], v[198:201], v[44:47]
	v_mfma_f32_16x16x32_bf16 v[40:43], v[166:169], v[198:201], v[40:43]
	v_mfma_f32_16x16x32_bf16 v[28:31], v[158:161], v[206:209], v[28:31]
	v_mfma_f32_16x16x32_bf16 v[24:27], v[166:169], v[206:209], v[24:27]
	v_mfma_f32_16x16x32_bf16 v[12:15], v[158:161], v[218:221], v[12:15]
	v_mfma_f32_16x16x32_bf16 v[8:11], v[166:169], v[218:221], v[8:11]
	v_mfma_f32_16x16x32_bf16 v[52:55], v[170:173], v[186:189], v[52:55]
	v_mfma_f32_16x16x32_bf16 v[48:51], v[178:181], v[186:189], v[48:51]
	v_mfma_f32_16x16x32_bf16 v[36:39], v[170:173], v[194:197], v[36:39]
	v_mfma_f32_16x16x32_bf16 v[32:35], v[178:181], v[194:197], v[32:35]
	v_mfma_f32_16x16x32_bf16 v[20:23], v[170:173], v[202:205], v[20:23]
	v_mfma_f32_16x16x32_bf16 v[16:19], v[178:181], v[202:205], v[16:19]
	v_mfma_f32_16x16x32_bf16 v[4:7], v[170:173], v[214:217], v[4:7]
	v_mfma_f32_16x16x32_bf16 v[0:3], v[178:181], v[214:217], v[0:3]
	v_mfma_f32_16x16x32_bf16 v[52:55], v[174:177], v[190:193], v[52:55]
	v_mfma_f32_16x16x32_bf16 v[48:51], v[182:185], v[190:193], v[48:51]
	v_mfma_f32_16x16x32_bf16 v[36:39], v[174:177], v[198:201], v[36:39]
	v_mfma_f32_16x16x32_bf16 v[32:35], v[182:185], v[198:201], v[32:35]
	v_mfma_f32_16x16x32_bf16 v[20:23], v[174:177], v[206:209], v[20:23]
	v_mfma_f32_16x16x32_bf16 v[16:19], v[182:185], v[206:209], v[16:19]
	v_mfma_f32_16x16x32_bf16 v[4:7], v[174:177], v[218:221], v[4:7]
	v_mfma_f32_16x16x32_bf16 v[0:3], v[182:185], v[218:221], v[0:3]
	s_setprio 0
	s_barrier
	s_add_i32 s73, s73, 2
	s_add_u32 s26, s26, 0x100
	s_addc_u32 s27, s27, 0
	s_add_u32 s71, s71, 0x100
	s_addc_u32 s72, s72, 0
	s_cmp_gt_u32 s73, 13
	s_cbranch_scc0 .LBB0_1026
	s_and_b64 vcc, exec, s[12:13]
	s_cbranch_vccz .LBB0_1029
	s_barrier

; #define PG8_STAGE(bufoff, gbase, voff) do { _Pragma("unroll") for (int _i = 0; _i < 2; ++_i) \
;         __builtin_amdgcn_global_load_lds((const unsigned*)((const char*)(gbase) + (voff)[_i]), (PG8_LAS unsigned*)(lds + (bufoff) + ldsw + _i * 8192), 16, 0, 0); } while (0)
; #define PG8_LDA(dst, b, h) do { _Pragma("unroll") for (int m = 0; m < 4; ++m) _Pragma("unroll") for (int k = 0; k < 2; ++k) dst[m][k] = *(const PG8_LAS bf16x8*)(lds + PG8_SA(b, h) + aoff + m * 2048 + k * 1024); } while (0)
; #define PG8_LDB(dst, b, h) do { _Pragma("unroll") for (int n = 0; n < 2; ++n) _Pragma("unroll") for (int k = 0; k < 2; ++k) dst[n][k] = *(const PG8_LAS bf16x8*)(lds + PG8_SB(b, h) + boff + n * 2048 + k * 1024); } while (0)
; #define PG8_MMA(ai, bj, At, Bt) do { __builtin_amdgcn_s_setprio(1); _Pragma("unroll") for (int m = 0; m < 4; ++m) _Pragma("unroll") for (int n = 0; n < 2; ++n) _Pragma("unroll") for (int k = 0; k < 2; ++k) \
;         acc[ai][bj][m][n] = __builtin_amdgcn_mfma_f32_16x16x32_bf16(Bt[n][k], At[m][k], acc[ai][bj][m][n], 0, 0, 0); __builtin_amdgcn_s_setprio(0); } while (0)
; #define PG8_WAIT_V(n) asm volatile("s_waitcnt vmcnt(" #n ")" ::: "memory")
; #define PG8_WAIT_L(n) asm volatile("s_waitcnt lgkmcnt(" #n ")" ::: "memory")
; #define PG8_BAR __builtin_amdgcn_s_barrier()
; #define PG8_SCHED __builtin_amdgcn_sched_barrier(0)
; template <class Epi, class Sched, bool ALIGN_EPI = false, bool SP2 = false>
; __device__ __forceinline__ void gemm_phase(PG8_LAS unsigned char* lds, const Gemm g, const Sched& S, const Epi& E, int wave_s) {
;     ...
;             PG8_LDB(B0, 0, 0); PG8_LDB(B1, 0, 1); PG8_SCHED; PG8_LDA(At, 0, 0); PG8_STAGE(PG8_SA(1, 1), a1 + hstep, voffA);
;             PG8_WAIT_V(8); PG8_WAIT_L(0); PG8_BAR; PG8_MMA(0, 0, At, B0); PG8_MMA(0, 1, At, B1); PG8_BAR; PG8_SCHED;
;             PG8_LDA(At, 0, 1); PG8_STAGE(PG8_SB(0, 0), b2, voffB); PG8_STAGE(PG8_SB(0, 1), b2 + hstep, voffB); PG8_STAGE(PG8_SA(0, 0), a2, voffA);
.LBB0_1053:
	ds_read_b128 v[146:149], v153
	ds_read_b128 v[158:161], v153 offset:1024
	ds_read_b128 v[162:165], v153 offset:2048
	ds_read_b128 v[166:169], v153 offset:3072
	ds_read_b128 v[170:173], v154
	ds_read_b128 v[174:177], v154 offset:1024
	ds_read_b128 v[178:181], v154 offset:2048
	ds_read_b128 v[182:185], v154 offset:3072
	s_add_u32 s26, s24, 0xfffc0080
	s_addc_u32 s27, s25, -1
	s_cmp_eq_u32 s70, 12
	s_cselect_b32 s41, s17, s27
	s_cselect_b32 s40, s66, s26
	s_cselect_b32 s27, s13, s69
	s_cselect_b32 s26, s67, s68
	v_lshl_add_u64 v[210:211], s[24:25], 0, v[138:139]
	s_add_i32 m0, s23, 0xc000
	ds_read_b128 v[186:189], v155
	ds_read_b128 v[190:193], v155 offset:1024
	ds_read_b128 v[194:197], v155 offset:2048
	ds_read_b128 v[198:201], v155 offset:3072
	ds_read_b128 v[202:205], v155 offset:4096
	ds_read_b128 v[206:209], v155 offset:5120
	ds_read_b128 v[214:217], v155 offset:6144
	ds_read_b128 v[218:221], v155 offset:7168
	global_load_lds_dwordx4 v[210:211], off
	s_add_i32 m0, s23, 0xe000
	v_lshl_add_u64 v[210:211], s[24:25], 0, v[140:141]
	global_load_lds_dwordx4 v[210:211], off
	s_waitcnt vmcnt(8) lgkmcnt(0)
	s_barrier
	s_setprio 1
	v_mfma_f32_16x16x32_bf16 v[124:127], v[146:149], v[186:189], v[124:127]
	v_mfma_f32_16x16x32_bf16 v[120:123], v[162:165], v[186:189], v[120:123]
	v_mfma_f32_16x16x32_bf16 v[108:111], v[146:149], v[194:197], v[108:111]
	v_mfma_f32_16x16x32_bf16 v[104:107], v[162:165], v[194:197], v[104:107]
	v_mfma_f32_16x16x32_bf16 v[92:95], v[146:149], v[202:205], v[92:95]
	v_mfma_f32_16x16x32_bf16 v[88:91], v[162:165], v[202:205], v[88:91]
	v_mfma_f32_16x16x32_bf16 v[76:79], v[146:149], v[214:217], v[76:79]
	v_mfma_f32_16x16x32_bf16 v[72:75], v[162:165], v[214:217], v[72:75]
	v_mfma_f32_16x16x32_bf16 v[124:127], v[158:161], v[190:193], v[124:127]
	v_mfma_f32_16x16x32_bf16 v[120:123], v[166:169], v[190:193], v[120:123]
	v_mfma_f32_16x16x32_bf16 v[108:111], v[158:161], v[198:201], v[108:111]
	v_mfma_f32_16x16x32_bf16 v[104:107], v[166:169], v[198:201], v[104:107]
	v_mfma_f32_16x16x32_bf16 v[92:95], v[158:161], v[206:209], v[92:95]
	v_mfma_f32_16x16x32_bf16 v[88:91], v[166:169], v[206:209], v[88:91]
	v_mfma_f32_16x16x32_bf16 v[76:79], v[158:161], v[218:221], v[76:79]
	v_mfma_f32_16x16x32_bf16 v[72:75], v[166:169], v[218:221], v[72:75]
	v_mfma_f32_16x16x32_bf16 v[116:119], v[170:173], v[186:189], v[116:119]
	v_mfma_f32_16x16x32_bf16 v[112:115], v[178:181], v[186:189], v[112:115]
	v_mfma_f32_16x16x32_bf16 v[100:103], v[170:173], v[194:197], v[100:103]
	v_mfma_f32_16x16x32_bf16 v[96:99], v[178:181], v[194:197], v[96:99]
	v_mfma_f32_16x16x32_bf16 v[84:87], v[170:173], v[202:205], v[84:87]
	v_mfma_f32_16x16x32_bf16 v[80:83], v[178:181], v[202:205], v[80:83]
	v_mfma_f32_16x16x32_bf16 v[68:71], v[170:173], v[214:217], v[68:71]
	v_mfma_f32_16x16x32_bf16 v[64:67], v[178:181], v[214:217], v[64:67]
	v_mfma_f32_16x16x32_bf16 v[116:119], v[174:177], v[190:193], v[116:119]
	v_mfma_f32_16x16x32_bf16 v[112:115], v[182:185], v[190:193], v[112:115]
	v_mfma_f32_16x16x32_bf16 v[100:103], v[174:177], v[198:201], v[100:103]
	v_mfma_f32_16x16x32_bf16 v[96:99], v[182:185], v[198:201], v[96:99]
	v_mfma_f32_16x16x32_bf16 v[84:87], v[174:177], v[206:209], v[84:87]
	v_mfma_f32_16x16x32_bf16 v[80:83], v[182:185], v[206:209], v[80:83]
	v_mfma_f32_16x16x32_bf16 v[68:71], v[174:177], v[218:221], v[68:71]
	v_mfma_f32_16x16x32_bf16 v[64:67], v[182:185], v[218:221], v[64:67]
	s_setprio 0
	s_barrier
	s_add_i32 s71, s59, s46
	v_lshl_add_u64 v[210:211], s[26:27], 0, v[130:131]
	s_mov_b32 m0, s71
	ds_read_b128 v[186:189], v155 offset:16384
	ds_read_b128 v[190:193], v155 offset:17408
	ds_read_b128 v[194:197], v155 offset:18432
	ds_read_b128 v[198:201], v155 offset:19456
	ds_read_b128 v[202:205], v155 offset:20480
	ds_read_b128 v[206:209], v155 offset:21504
	ds_read_b128 v[214:217], v155 offset:22528
	ds_read_b128 v[218:221], v155 offset:23552
	global_load_lds_dwordx4 v[210:211], off
	s_add_i32 m0, s71, 0x2000
	s_add_u32 s72, s26, 0x40000
	v_lshl_add_u64 v[222:223], s[26:27], 0, v[134:135]
	s_addc_u32 s73, s27, 0
	s_add_i32 s71, s60, s46
	global_load_lds_dwordx4 v[222:223], off
	v_lshl_add_u64 v[224:225], s[72:73], 0, v[130:131]
	s_mov_b32 m0, s71
	v_lshl_add_u64 v[226:227], s[40:41], 0, v[132:133]
	global_load_lds_dwordx4 v[224:225], off
	s_add_i32 m0, s71, 0x2000
	v_lshl_add_u64 v[224:225], s[72:73], 0, v[134:135]
	global_load_lds_dwordx4 v[224:225], off
	s_mov_b32 m0, s23
	v_lshl_add_u64 v[224:225], s[40:41], 0, v[128:129]
	global_load_lds_dwordx4 v[224:225], off
	s_mov_b32 m0, s47
	s_nop 0
	global_load_lds_dwordx4 v[226:227], off
	s_waitcnt vmcnt(8) lgkmcnt(0)
	s_barrier
; #define PG8_STAGE(bufoff, gbase, voff) do { _Pragma("unroll") for (int _i = 0; _i < 2; ++_i) \
;         __builtin_amdgcn_global_load_lds((const unsigned*)((const char*)(gbase) + (voff)[_i]), (PG8_LAS unsigned*)(lds + (bufoff) + ldsw + _i * 8192), 16, 0, 0); } while (0)
; #define PG8_LDA(dst, b, h) do { _Pragma("unroll") for (int m = 0; m < 4; ++m) _Pragma("unroll") for (int k = 0; k < 2; ++k) dst[m][k] = *(const PG8_LAS bf16x8*)(lds + PG8_SA(b, h) + aoff + m * 2048 + k * 1024); } while (0)
; #define PG8_LDB(dst, b, h) do { _Pragma("unroll") for (int n = 0; n < 2; ++n) _Pragma("unroll") for (int k = 0; k < 2; ++k) dst[n][k] = *(const PG8_LAS bf16x8*)(lds + PG8_SB(b, h) + boff + n * 2048 + k * 1024); } while (0)
; #define PG8_MMA(ai, bj, At, Bt) do { __builtin_amdgcn_s_setprio(1); _Pragma("unroll") for (int m = 0; m < 4; ++m) _Pragma("unroll") for (int n = 0; n < 2; ++n) _Pragma("unroll") for (int k = 0; k < 2; ++k) \
;         acc[ai][bj][m][n] = __builtin_amdgcn_mfma_f32_16x16x32_bf16(Bt[n][k], At[m][k], acc[ai][bj][m][n], 0, 0, 0); __builtin_amdgcn_s_setprio(0); } while (0)
; #define PG8_WAIT_V(n) asm volatile("s_waitcnt vmcnt(" #n ")" ::: "memory")
; #define PG8_WAIT_L(n) asm volatile("s_waitcnt lgkmcnt(" #n ")" ::: "memory")
; #define PG8_BAR __builtin_amdgcn_s_barrier()
; #define PG8_SCHED __builtin_amdgcn_sched_barrier(0)
; template <class Epi, class Sched, bool ALIGN_EPI = false, bool SP2 = false>
; __device__ __forceinline__ void gemm_phase(PG8_LAS unsigned char* lds, const Gemm g, const Sched& S, const Epi& E, int wave_s) {
;     ...
;             PG8_WAIT_V(8); PG8_WAIT_L(0); PG8_BAR; PG8_MMA(1, 0, At, B0); PG8_MMA(1, 1, At, B1); PG8_BAR; PG8_SCHED;
;             PG8_LDB(B0, 1, 0); PG8_LDB(B1, 1, 1); PG8_SCHED; PG8_LDA(At, 1, 0); PG8_STAGE(PG8_SA(0, 1), a2 + hstep, voffA);
;             PG8_WAIT_V(8); PG8_WAIT_L(0); PG8_BAR; PG8_MMA(0, 0, At, B0); PG8_MMA(0, 1, At, B1); PG8_BAR; PG8_SCHED;
	s_setprio 1
	v_mfma_f32_16x16x32_bf16 v[60:63], v[146:149], v[186:189], v[60:63]
	v_mfma_f32_16x16x32_bf16 v[56:59], v[162:165], v[186:189], v[56:59]
	v_mfma_f32_16x16x32_bf16 v[44:47], v[146:149], v[194:197], v[44:47]
	v_mfma_f32_16x16x32_bf16 v[40:43], v[162:165], v[194:197], v[40:43]
	v_mfma_f32_16x16x32_bf16 v[28:31], v[146:149], v[202:205], v[28:31]
	v_mfma_f32_16x16x32_bf16 v[24:27], v[162:165], v[202:205], v[24:27]
	v_mfma_f32_16x16x32_bf16 v[12:15], v[146:149], v[214:217], v[12:15]
	v_mfma_f32_16x16x32_bf16 v[8:11], v[162:165], v[214:217], v[8:11]
	v_mfma_f32_16x16x32_bf16 v[60:63], v[158:161], v[190:193], v[60:63]
	v_mfma_f32_16x16x32_bf16 v[56:59], v[166:169], v[190:193], v[56:59]
	v_mfma_f32_16x16x32_bf16 v[44:47], v[158:161], v[198:201], v[44:47]
	v_mfma_f32_16x16x32_bf16 v[40:43], v[166:169], v[198:201], v[40:43]
	v_mfma_f32_16x16x32_bf16 v[28:31], v[158:161], v[206:209], v[28:31]
	v_mfma_f32_16x16x32_bf16 v[24:27], v[166:169], v[206:209], v[24:27]
	v_mfma_f32_16x16x32_bf16 v[12:15], v[158:161], v[218:221], v[12:15]
	v_mfma_f32_16x16x32_bf16 v[8:11], v[166:169], v[218:221], v[8:11]
	v_mfma_f32_16x16x32_bf16 v[52:55], v[170:173], v[186:189], v[52:55]
	v_mfma_f32_16x16x32_bf16 v[48:51], v[178:181], v[186:189], v[48:51]
	v_mfma_f32_16x16x32_bf16 v[36:39], v[170:173], v[194:197], v[36:39]
	v_mfma_f32_16x16x32_bf16 v[32:35], v[178:181], v[194:197], v[32:35]
	v_mfma_f32_16x16x32_bf16 v[20:23], v[170:173], v[202:205], v[20:23]
	v_mfma_f32_16x16x32_bf16 v[16:19], v[178:181], v[202:205], v[16:19]
	v_mfma_f32_16x16x32_bf16 v[4:7], v[170:173], v[214:217], v[4:7]
	v_mfma_f32_16x16x32_bf16 v[0:3], v[178:181], v[214:217], v[0:3]
	v_mfma_f32_16x16x32_bf16 v[52:55], v[174:177], v[190:193], v[52:55]
	v_mfma_f32_16x16x32_bf16 v[48:51], v[182:185], v[190:193], v[48:51]
	v_mfma_f32_16x16x32_bf16 v[36:39], v[174:177], v[198:201], v[36:39]
	v_mfma_f32_16x16x32_bf16 v[32:35], v[182:185], v[198:201], v[32:35]
	v_mfma_f32_16x16x32_bf16 v[20:23], v[174:177], v[206:209], v[20:23]
	v_mfma_f32_16x16x32_bf16 v[16:19], v[182:185], v[206:209], v[16:19]
	v_mfma_f32_16x16x32_bf16 v[4:7], v[174:177], v[218:221], v[4:7]
	v_mfma_f32_16x16x32_bf16 v[0:3], v[182:185], v[218:221], v[0:3]
	s_setprio 0
	s_barrier
	s_add_i32 s71, 0, 0x18000
	v_add_u32_e32 v136, s71, v151
	s_add_i32 s72, 0, 0x1c000
	ds_read_b128 v[146:149], v136
	ds_read_b128 v[158:161], v136 offset:1024
	ds_read_b128 v[162:165], v136 offset:2048
	ds_read_b128 v[166:169], v136 offset:3072
	v_add_u32_e32 v136, s72, v151
	ds_read_b128 v[170:173], v136
	ds_read_b128 v[174:177], v136 offset:1024
	ds_read_b128 v[178:181], v136 offset:2048
	ds_read_b128 v[182:185], v136 offset:3072
	s_add_u32 s40, s40, 0x40000
	s_addc_u32 s41, s41, 0
	s_mov_b32 m0, s48
	v_lshl_add_u64 v[228:229], s[40:41], 0, v[128:129]
	ds_read_b128 v[186:189], v155 offset:32768
	ds_read_b128 v[190:193], v155 offset:33792
	ds_read_b128 v[194:197], v155 offset:34816
	ds_read_b128 v[198:201], v155 offset:35840
	ds_read_b128 v[202:205], v155 offset:36864
	ds_read_b128 v[206:209], v155 offset:37888
	ds_read_b128 v[214:217], v155 offset:38912
	ds_read_b128 v[218:221], v155 offset:39936
	global_load_lds_dwordx4 v[228:229], off
	s_mov_b32 m0, s49
	v_lshl_add_u64 v[228:229], s[40:41], 0, v[132:133]
	global_load_lds_dwordx4 v[228:229], off
	s_waitcnt vmcnt(8) lgkmcnt(0)
	s_barrier
	s_setprio 1
	v_mfma_f32_16x16x32_bf16 v[124:127], v[146:149], v[186:189], v[124:127]
	v_mfma_f32_16x16x32_bf16 v[120:123], v[162:165], v[186:189], v[120:123]
	v_mfma_f32_16x16x32_bf16 v[108:111], v[146:149], v[194:197], v[108:111]
	v_mfma_f32_16x16x32_bf16 v[104:107], v[162:165], v[194:197], v[104:107]
	v_mfma_f32_16x16x32_bf16 v[92:95], v[146:149], v[202:205], v[92:95]
	v_mfma_f32_16x16x32_bf16 v[88:91], v[162:165], v[202:205], v[88:91]
	v_mfma_f32_16x16x32_bf16 v[76:79], v[146:149], v[214:217], v[76:79]
	v_mfma_f32_16x16x32_bf16 v[72:75], v[162:165], v[214:217], v[72:75]
	v_mfma_f32_16x16x32_bf16 v[124:127], v[158:161], v[190:193], v[124:127]
	v_mfma_f32_16x16x32_bf16 v[120:123], v[166:169], v[190:193], v[120:123]
	v_mfma_f32_16x16x32_bf16 v[108:111], v[158:161], v[198:201], v[108:111]
	v_mfma_f32_16x16x32_bf16 v[104:107], v[166:169], v[198:201], v[104:107]
	v_mfma_f32_16x16x32_bf16 v[92:95], v[158:161], v[206:209], v[92:95]
	v_mfma_f32_16x16x32_bf16 v[88:91], v[166:169], v[206:209], v[88:91]
	v_mfma_f32_16x16x32_bf16 v[76:79], v[158:161], v[218:221], v[76:79]
	v_mfma_f32_16x16x32_bf16 v[72:75], v[166:169], v[218:221], v[72:75]
	v_mfma_f32_16x16x32_bf16 v[116:119], v[170:173], v[186:189], v[116:119]
	v_mfma_f32_16x16x32_bf16 v[112:115], v[178:181], v[186:189], v[112:115]
	v_mfma_f32_16x16x32_bf16 v[100:103], v[170:173], v[194:197], v[100:103]
	v_mfma_f32_16x16x32_bf16 v[96:99], v[178:181], v[194:197], v[96:99]
	v_mfma_f32_16x16x32_bf16 v[84:87], v[170:173], v[202:205], v[84:87]
	v_mfma_f32_16x16x32_bf16 v[80:83], v[178:181], v[202:205], v[80:83]
	v_mfma_f32_16x16x32_bf16 v[68:71], v[170:173], v[214:217], v[68:71]
	v_mfma_f32_16x16x32_bf16 v[64:67], v[178:181], v[214:217], v[64:67]
	v_mfma_f32_16x16x32_bf16 v[116:119], v[174:177], v[190:193], v[116:119]
	v_mfma_f32_16x16x32_bf16 v[112:115], v[182:185], v[190:193], v[112:115]
	v_mfma_f32_16x16x32_bf16 v[100:103], v[174:177], v[198:201], v[100:103]
	v_mfma_f32_16x16x32_bf16 v[96:99], v[182:185], v[198:201], v[96:99]
	v_mfma_f32_16x16x32_bf16 v[84:87], v[174:177], v[206:209], v[84:87]
	v_mfma_f32_16x16x32_bf16 v[80:83], v[182:185], v[206:209], v[80:83]
	v_mfma_f32_16x16x32_bf16 v[68:71], v[174:177], v[218:221], v[68:71]
	v_mfma_f32_16x16x32_bf16 v[64:67], v[182:185], v[218:221], v[64:67]
	s_setprio 0
	s_barrier
; #define PG8_STAGE(bufoff, gbase, voff) do { _Pragma("unroll") for (int _i = 0; _i < 2; ++_i) \
;         __builtin_amdgcn_global_load_lds((const unsigned*)((const char*)(gbase) + (voff)[_i]), (PG8_LAS unsigned*)(lds + (bufoff) + ldsw + _i * 8192), 16, 0, 0); } while (0)
; #define PG8_LDA(dst, b, h) do { _Pragma("unroll") for (int m = 0; m < 4; ++m) _Pragma("unroll") for (int k = 0; k < 2; ++k) dst[m][k] = *(const PG8_LAS bf16x8*)(lds + PG8_SA(b, h) + aoff + m * 2048 + k * 1024); } while (0)
; #define PG8_MMA(ai, bj, At, Bt) do { __builtin_amdgcn_s_setprio(1); _Pragma("unroll") for (int m = 0; m < 4; ++m) _Pragma("unroll") for (int n = 0; n < 2; ++n) _Pragma("unroll") for (int k = 0; k < 2; ++k) \
;         acc[ai][bj][m][n] = __builtin_amdgcn_mfma_f32_16x16x32_bf16(Bt[n][k], At[m][k], acc[ai][bj][m][n], 0, 0, 0); __builtin_amdgcn_s_setprio(0); } while (0)
; #define PG8_WAIT_V(n) asm volatile("s_waitcnt vmcnt(" #n ")" ::: "memory")
; #define PG8_WAIT_L(n) asm volatile("s_waitcnt lgkmcnt(" #n ")" ::: "memory")
; #define PG8_BAR __builtin_amdgcn_s_barrier()
; #define PG8_SCHED __builtin_amdgcn_sched_barrier(0)
; template <class Epi, class Sched, bool ALIGN_EPI = false, bool SP2 = false>
; __device__ __forceinline__ void gemm_phase(PG8_LAS unsigned char* lds, const Gemm g, const Sched& S, const Epi& E, int wave_s) {
;     ...
;         for (int t = 0; t < nt; t += 2) {
;             const bool last = (t == nt - 2);
;     ...
;             PG8_LDA(At, 1, 1); PG8_STAGE(PG8_SB(1, 0), b3, voffB); PG8_STAGE(PG8_SB(1, 1), b3 + hstep, voffB); PG8_STAGE(PG8_SA(1, 0), a3, voffA);
;             PG8_WAIT_V(8); PG8_WAIT_L(0); PG8_BAR; PG8_MMA(1, 0, At, B0); PG8_MMA(1, 1, At, B1); PG8_BAR; PG8_SCHED;
;     ...
;         if constexpr (ALIGN_EPI) { if (wr == 0) PG8_BAR; }
	s_add_i32 s40, s71, s46
	v_lshl_add_u64 v[210:211], v[210:211], 0, s[8:9]
	s_mov_b32 m0, s40
	ds_read_b128 v[186:189], v155 offset:49152
	ds_read_b128 v[190:193], v155 offset:50176
	ds_read_b128 v[194:197], v155 offset:51200
	ds_read_b128 v[198:201], v155 offset:52224
	ds_read_b128 v[202:205], v155 offset:53248
	ds_read_b128 v[206:209], v155 offset:54272
	ds_read_b128 v[214:217], v155 offset:55296
	ds_read_b128 v[218:221], v155 offset:56320
	global_load_lds_dwordx4 v[210:211], off
	s_add_i32 m0, s40, 0x2000
	s_add_u32 s26, s26, 0x40080
	v_lshl_add_u64 v[210:211], v[222:223], 0, s[8:9]
	s_addc_u32 s27, s27, 0
	s_add_i32 s40, s72, s46
	global_load_lds_dwordx4 v[210:211], off
	s_mov_b32 m0, s40
	v_lshl_add_u64 v[210:211], s[26:27], 0, v[130:131]
	global_load_lds_dwordx4 v[210:211], off
	s_add_i32 m0, s40, 0x2000
	v_lshl_add_u64 v[210:211], s[26:27], 0, v[134:135]
	global_load_lds_dwordx4 v[210:211], off
	s_mov_b32 m0, s51
	v_lshl_add_u64 v[210:211], v[224:225], 0, s[8:9]
	global_load_lds_dwordx4 v[210:211], off
	s_mov_b32 m0, s56
	v_lshl_add_u64 v[210:211], v[226:227], 0, s[8:9]
	global_load_lds_dwordx4 v[210:211], off
	s_waitcnt vmcnt(8) lgkmcnt(0)
	s_barrier
	s_setprio 1
	v_mfma_f32_16x16x32_bf16 v[60:63], v[146:149], v[186:189], v[60:63]
	v_mfma_f32_16x16x32_bf16 v[56:59], v[162:165], v[186:189], v[56:59]
	v_mfma_f32_16x16x32_bf16 v[44:47], v[146:149], v[194:197], v[44:47]
	v_mfma_f32_16x16x32_bf16 v[40:43], v[162:165], v[194:197], v[40:43]
	v_mfma_f32_16x16x32_bf16 v[28:31], v[146:149], v[202:205], v[28:31]
	v_mfma_f32_16x16x32_bf16 v[24:27], v[162:165], v[202:205], v[24:27]
	v_mfma_f32_16x16x32_bf16 v[12:15], v[146:149], v[214:217], v[12:15]
	v_mfma_f32_16x16x32_bf16 v[8:11], v[162:165], v[214:217], v[8:11]
	v_mfma_f32_16x16x32_bf16 v[60:63], v[158:161], v[190:193], v[60:63]
	v_mfma_f32_16x16x32_bf16 v[56:59], v[166:169], v[190:193], v[56:59]
	v_mfma_f32_16x16x32_bf16 v[44:47], v[158:161], v[198:201], v[44:47]
	v_mfma_f32_16x16x32_bf16 v[40:43], v[166:169], v[198:201], v[40:43]
	v_mfma_f32_16x16x32_bf16 v[28:31], v[158:161], v[206:209], v[28:31]
	v_mfma_f32_16x16x32_bf16 v[24:27], v[166:169], v[206:209], v[24:27]
	v_mfma_f32_16x16x32_bf16 v[12:15], v[158:161], v[218:221], v[12:15]
	v_mfma_f32_16x16x32_bf16 v[8:11], v[166:169], v[218:221], v[8:11]
	v_mfma_f32_16x16x32_bf16 v[52:55], v[170:173], v[186:189], v[52:55]
	v_mfma_f32_16x16x32_bf16 v[48:51], v[178:181], v[186:189], v[48:51]
	v_mfma_f32_16x16x32_bf16 v[36:39], v[170:173], v[194:197], v[36:39]
	v_mfma_f32_16x16x32_bf16 v[32:35], v[178:181], v[194:197], v[32:35]
	v_mfma_f32_16x16x32_bf16 v[20:23], v[170:173], v[202:205], v[20:23]
	v_mfma_f32_16x16x32_bf16 v[16:19], v[178:181], v[202:205], v[16:19]
	v_mfma_f32_16x16x32_bf16 v[4:7], v[170:173], v[214:217], v[4:7]
	v_mfma_f32_16x16x32_bf16 v[0:3], v[178:181], v[214:217], v[0:3]
	v_mfma_f32_16x16x32_bf16 v[52:55], v[174:177], v[190:193], v[52:55]
	v_mfma_f32_16x16x32_bf16 v[48:51], v[182:185], v[190:193], v[48:51]
	v_mfma_f32_16x16x32_bf16 v[36:39], v[174:177], v[198:201], v[36:39]
	v_mfma_f32_16x16x32_bf16 v[32:35], v[182:185], v[198:201], v[32:35]
	v_mfma_f32_16x16x32_bf16 v[20:23], v[174:177], v[206:209], v[20:23]
	v_mfma_f32_16x16x32_bf16 v[16:19], v[182:185], v[206:209], v[16:19]
	v_mfma_f32_16x16x32_bf16 v[4:7], v[174:177], v[218:221], v[4:7]
	v_mfma_f32_16x16x32_bf16 v[0:3], v[182:185], v[218:221], v[0:3]
	s_setprio 0
	s_barrier
	s_add_i32 s70, s70, 2
	s_add_u32 s24, s24, 0x100
	s_addc_u32 s25, s25, 0
	s_add_u32 s68, s68, 0x100
	s_addc_u32 s69, s69, 0
	s_cmp_gt_u32 s70, 13
	s_cbranch_scc0 .LBB0_1053
	s_and_b64 vcc, exec, s[10:11]
	s_cbranch_vccz .LBB0_1056
	s_barrier

; #define PG8_STAGE(bufoff, gbase, voff) do { _Pragma("unroll") for (int _i = 0; _i < 2; ++_i) \
;         __builtin_amdgcn_global_load_lds((const unsigned*)((const char*)(gbase) + (voff)[_i]), (PG8_LAS unsigned*)(lds + (bufoff) + ldsw + _i * 8192), 16, 0, 0); } while (0)
; #define PG8_LDA(dst, b, h) do { _Pragma("unroll") for (int m = 0; m < 4; ++m) _Pragma("unroll") for (int k = 0; k < 2; ++k) dst[m][k] = *(const PG8_LAS bf16x8*)(lds + PG8_SA(b, h) + aoff + m * 2048 + k * 1024); } while (0)
; #define PG8_LDB(dst, b, h) do { _Pragma("unroll") for (int n = 0; n < 2; ++n) _Pragma("unroll") for (int k = 0; k < 2; ++k) dst[n][k] = *(const PG8_LAS bf16x8*)(lds + PG8_SB(b, h) + boff + n * 2048 + k * 1024); } while (0)
; #define PG8_MMA(ai, bj, At, Bt) do { __builtin_amdgcn_s_setprio(1); _Pragma("unroll") for (int m = 0; m < 4; ++m) _Pragma("unroll") for (int n = 0; n < 2; ++n) _Pragma("unroll") for (int k = 0; k < 2; ++k) \
;         acc[ai][bj][m][n] = __builtin_amdgcn_mfma_f32_16x16x32_bf16(Bt[n][k], At[m][k], acc[ai][bj][m][n], 0, 0, 0); __builtin_amdgcn_s_setprio(0); } while (0)
; #define PG8_WAIT_V(n) asm volatile("s_waitcnt vmcnt(" #n ")" ::: "memory")
; #define PG8_WAIT_L(n) asm volatile("s_waitcnt lgkmcnt(" #n ")" ::: "memory")
; #define PG8_BAR __builtin_amdgcn_s_barrier()
; #define PG8_SCHED __builtin_amdgcn_sched_barrier(0)
; template <class Epi, class Sched, bool ALIGN_EPI = false, bool SP2 = false>
; __device__ __forceinline__ void gemm_phase(PG8_LAS unsigned char* lds, const Gemm g, const Sched& S, const Epi& E, int wave_s) {
;     ...
;             PG8_LDB(B0, 0, 0); PG8_LDB(B1, 0, 1); PG8_SCHED; PG8_LDA(At, 0, 0); PG8_STAGE(PG8_SA(1, 1), a1 + hstep, voffA);
;             PG8_WAIT_V(8); PG8_WAIT_L(0); PG8_BAR; PG8_MMA(0, 0, At, B0); PG8_MMA(0, 1, At, B1); PG8_BAR; PG8_SCHED;
;             PG8_LDA(At, 0, 1); PG8_STAGE(PG8_SB(0, 0), b2, voffB); PG8_STAGE(PG8_SB(0, 1), b2 + hstep, voffB); PG8_STAGE(PG8_SA(0, 0), a2, voffA);
.LBB0_1138:
	ds_read_b128 v[146:149], v155
	ds_read_b128 v[158:161], v155 offset:1024
	ds_read_b128 v[162:165], v155 offset:2048
	ds_read_b128 v[166:169], v155 offset:3072
	ds_read_b128 v[170:173], v156
	ds_read_b128 v[174:177], v156 offset:1024
	ds_read_b128 v[178:181], v156 offset:2048
	ds_read_b128 v[182:185], v156 offset:3072
	s_add_u32 s44, s42, 0xfffc0080
	s_addc_u32 s45, s43, -1
	s_cmp_eq_u32 s75, 12
	s_cselect_b32 s47, s21, s45
	s_cselect_b32 s46, s27, s44
	s_cselect_b32 s45, s19, s74
	s_cselect_b32 s44, s41, s73
	v_lshl_add_u64 v[150:151], s[42:43], 0, v[138:139]
	s_add_i32 m0, s51, 0xc000
	ds_read_b128 v[186:189], v157
	ds_read_b128 v[190:193], v157 offset:1024
	ds_read_b128 v[194:197], v157 offset:2048
	ds_read_b128 v[198:201], v157 offset:3072
	ds_read_b128 v[202:205], v157 offset:4096
	ds_read_b128 v[206:209], v157 offset:5120
	ds_read_b128 v[214:217], v157 offset:6144
	ds_read_b128 v[218:221], v157 offset:7168
	global_load_lds_dwordx4 v[150:151], off
	s_add_i32 m0, s51, 0xe000
	v_lshl_add_u64 v[150:151], s[42:43], 0, v[140:141]
	global_load_lds_dwordx4 v[150:151], off
	s_waitcnt vmcnt(8) lgkmcnt(0)
	s_barrier
	s_setprio 1
	v_mfma_f32_16x16x32_bf16 v[124:127], v[146:149], v[186:189], v[124:127]
	v_mfma_f32_16x16x32_bf16 v[120:123], v[162:165], v[186:189], v[120:123]
	v_mfma_f32_16x16x32_bf16 v[108:111], v[146:149], v[194:197], v[108:111]
	v_mfma_f32_16x16x32_bf16 v[104:107], v[162:165], v[194:197], v[104:107]
	v_mfma_f32_16x16x32_bf16 v[92:95], v[146:149], v[202:205], v[92:95]
	v_mfma_f32_16x16x32_bf16 v[88:91], v[162:165], v[202:205], v[88:91]
	v_mfma_f32_16x16x32_bf16 v[76:79], v[146:149], v[214:217], v[76:79]
	v_mfma_f32_16x16x32_bf16 v[72:75], v[162:165], v[214:217], v[72:75]
	v_mfma_f32_16x16x32_bf16 v[124:127], v[158:161], v[190:193], v[124:127]
	v_mfma_f32_16x16x32_bf16 v[120:123], v[166:169], v[190:193], v[120:123]
	v_mfma_f32_16x16x32_bf16 v[108:111], v[158:161], v[198:201], v[108:111]
	v_mfma_f32_16x16x32_bf16 v[104:107], v[166:169], v[198:201], v[104:107]
	v_mfma_f32_16x16x32_bf16 v[92:95], v[158:161], v[206:209], v[92:95]
	v_mfma_f32_16x16x32_bf16 v[88:91], v[166:169], v[206:209], v[88:91]
	v_mfma_f32_16x16x32_bf16 v[76:79], v[158:161], v[218:221], v[76:79]
	v_mfma_f32_16x16x32_bf16 v[72:75], v[166:169], v[218:221], v[72:75]
	v_mfma_f32_16x16x32_bf16 v[116:119], v[170:173], v[186:189], v[116:119]
	v_mfma_f32_16x16x32_bf16 v[112:115], v[178:181], v[186:189], v[112:115]
	v_mfma_f32_16x16x32_bf16 v[100:103], v[170:173], v[194:197], v[100:103]
	v_mfma_f32_16x16x32_bf16 v[96:99], v[178:181], v[194:197], v[96:99]
	v_mfma_f32_16x16x32_bf16 v[84:87], v[170:173], v[202:205], v[84:87]
	v_mfma_f32_16x16x32_bf16 v[80:83], v[178:181], v[202:205], v[80:83]
	v_mfma_f32_16x16x32_bf16 v[68:71], v[170:173], v[214:217], v[68:71]
	v_mfma_f32_16x16x32_bf16 v[64:67], v[178:181], v[214:217], v[64:67]
	v_mfma_f32_16x16x32_bf16 v[116:119], v[174:177], v[190:193], v[116:119]
	v_mfma_f32_16x16x32_bf16 v[112:115], v[182:185], v[190:193], v[112:115]
	v_mfma_f32_16x16x32_bf16 v[100:103], v[174:177], v[198:201], v[100:103]
	v_mfma_f32_16x16x32_bf16 v[96:99], v[182:185], v[198:201], v[96:99]
	v_mfma_f32_16x16x32_bf16 v[84:87], v[174:177], v[206:209], v[84:87]
	v_mfma_f32_16x16x32_bf16 v[80:83], v[182:185], v[206:209], v[80:83]
	v_mfma_f32_16x16x32_bf16 v[68:71], v[174:177], v[218:221], v[68:71]
	v_mfma_f32_16x16x32_bf16 v[64:67], v[182:185], v[218:221], v[64:67]
	s_setprio 0
	s_barrier
	s_add_i32 s76, s66, s50
	v_lshl_add_u64 v[150:151], s[44:45], 0, v[130:131]
	s_mov_b32 m0, s76
	ds_read_b128 v[186:189], v157 offset:16384
	ds_read_b128 v[190:193], v157 offset:17408
	ds_read_b128 v[194:197], v157 offset:18432
	ds_read_b128 v[198:201], v157 offset:19456
	ds_read_b128 v[202:205], v157 offset:20480
	ds_read_b128 v[206:209], v157 offset:21504
	ds_read_b128 v[214:217], v157 offset:22528
	ds_read_b128 v[218:221], v157 offset:23552
	global_load_lds_dwordx4 v[150:151], off
	s_add_i32 m0, s76, 0x2000
	s_add_u32 s76, s44, 0x40000
	v_lshl_add_u64 v[210:211], s[44:45], 0, v[134:135]
	s_addc_u32 s77, s45, 0
	s_add_i32 s78, s67, s50
	global_load_lds_dwordx4 v[210:211], off
	v_lshl_add_u64 v[222:223], s[76:77], 0, v[130:131]
	s_mov_b32 m0, s78
	v_lshl_add_u64 v[224:225], s[46:47], 0, v[132:133]
	global_load_lds_dwordx4 v[222:223], off
	s_add_i32 m0, s78, 0x2000
	v_lshl_add_u64 v[222:223], s[76:77], 0, v[134:135]
	global_load_lds_dwordx4 v[222:223], off
	s_mov_b32 m0, s51
	v_lshl_add_u64 v[222:223], s[46:47], 0, v[128:129]
	global_load_lds_dwordx4 v[222:223], off
	s_mov_b32 m0, s56
	s_nop 0
	global_load_lds_dwordx4 v[224:225], off
	s_waitcnt vmcnt(8) lgkmcnt(0)
	s_barrier
; #define PG8_STAGE(bufoff, gbase, voff) do { _Pragma("unroll") for (int _i = 0; _i < 2; ++_i) \
;         __builtin_amdgcn_global_load_lds((const unsigned*)((const char*)(gbase) + (voff)[_i]), (PG8_LAS unsigned*)(lds + (bufoff) + ldsw + _i * 8192), 16, 0, 0); } while (0)
; #define PG8_LDA(dst, b, h) do { _Pragma("unroll") for (int m = 0; m < 4; ++m) _Pragma("unroll") for (int k = 0; k < 2; ++k) dst[m][k] = *(const PG8_LAS bf16x8*)(lds + PG8_SA(b, h) + aoff + m * 2048 + k * 1024); } while (0)
; #define PG8_LDB(dst, b, h) do { _Pragma("unroll") for (int n = 0; n < 2; ++n) _Pragma("unroll") for (int k = 0; k < 2; ++k) dst[n][k] = *(const PG8_LAS bf16x8*)(lds + PG8_SB(b, h) + boff + n * 2048 + k * 1024); } while (0)
; #define PG8_MMA(ai, bj, At, Bt) do { __builtin_amdgcn_s_setprio(1); _Pragma("unroll") for (int m = 0; m < 4; ++m) _Pragma("unroll") for (int n = 0; n < 2; ++n) _Pragma("unroll") for (int k = 0; k < 2; ++k) \
;         acc[ai][bj][m][n] = __builtin_amdgcn_mfma_f32_16x16x32_bf16(Bt[n][k], At[m][k], acc[ai][bj][m][n], 0, 0, 0); __builtin_amdgcn_s_setprio(0); } while (0)
; #define PG8_WAIT_V(n) asm volatile("s_waitcnt vmcnt(" #n ")" ::: "memory")
; #define PG8_WAIT_L(n) asm volatile("s_waitcnt lgkmcnt(" #n ")" ::: "memory")
; #define PG8_BAR __builtin_amdgcn_s_barrier()
; #define PG8_SCHED __builtin_amdgcn_sched_barrier(0)
; template <class Epi, class Sched, bool ALIGN_EPI = false, bool SP2 = false>
; __device__ __forceinline__ void gemm_phase(PG8_LAS unsigned char* lds, const Gemm g, const Sched& S, const Epi& E, int wave_s) {
;     ...
;             PG8_WAIT_V(8); PG8_WAIT_L(0); PG8_BAR; PG8_MMA(1, 0, At, B0); PG8_MMA(1, 1, At, B1); PG8_BAR; PG8_SCHED;
;             PG8_LDB(B0, 1, 0); PG8_LDB(B1, 1, 1); PG8_SCHED; PG8_LDA(At, 1, 0); PG8_STAGE(PG8_SA(0, 1), a2 + hstep, voffA);
;             PG8_WAIT_V(8); PG8_WAIT_L(0); PG8_BAR; PG8_MMA(0, 0, At, B0); PG8_MMA(0, 1, At, B1); PG8_BAR; PG8_SCHED;
	s_setprio 1
	v_mfma_f32_16x16x32_bf16 v[60:63], v[146:149], v[186:189], v[60:63]
	v_mfma_f32_16x16x32_bf16 v[56:59], v[162:165], v[186:189], v[56:59]
	v_mfma_f32_16x16x32_bf16 v[44:47], v[146:149], v[194:197], v[44:47]
	v_mfma_f32_16x16x32_bf16 v[40:43], v[162:165], v[194:197], v[40:43]
	v_mfma_f32_16x16x32_bf16 v[28:31], v[146:149], v[202:205], v[28:31]
	v_mfma_f32_16x16x32_bf16 v[24:27], v[162:165], v[202:205], v[24:27]
	v_mfma_f32_16x16x32_bf16 v[12:15], v[146:149], v[214:217], v[12:15]
	v_mfma_f32_16x16x32_bf16 v[8:11], v[162:165], v[214:217], v[8:11]
	v_mfma_f32_16x16x32_bf16 v[60:63], v[158:161], v[190:193], v[60:63]
	v_mfma_f32_16x16x32_bf16 v[56:59], v[166:169], v[190:193], v[56:59]
	v_mfma_f32_16x16x32_bf16 v[44:47], v[158:161], v[198:201], v[44:47]
	v_mfma_f32_16x16x32_bf16 v[40:43], v[166:169], v[198:201], v[40:43]
	v_mfma_f32_16x16x32_bf16 v[28:31], v[158:161], v[206:209], v[28:31]
	v_mfma_f32_16x16x32_bf16 v[24:27], v[166:169], v[206:209], v[24:27]
	v_mfma_f32_16x16x32_bf16 v[12:15], v[158:161], v[218:221], v[12:15]
	v_mfma_f32_16x16x32_bf16 v[8:11], v[166:169], v[218:221], v[8:11]
	v_mfma_f32_16x16x32_bf16 v[52:55], v[170:173], v[186:189], v[52:55]
	v_mfma_f32_16x16x32_bf16 v[48:51], v[178:181], v[186:189], v[48:51]
	v_mfma_f32_16x16x32_bf16 v[36:39], v[170:173], v[194:197], v[36:39]
	v_mfma_f32_16x16x32_bf16 v[32:35], v[178:181], v[194:197], v[32:35]
	v_mfma_f32_16x16x32_bf16 v[20:23], v[170:173], v[202:205], v[20:23]
	v_mfma_f32_16x16x32_bf16 v[16:19], v[178:181], v[202:205], v[16:19]
	v_mfma_f32_16x16x32_bf16 v[4:7], v[170:173], v[214:217], v[4:7]
	v_mfma_f32_16x16x32_bf16 v[0:3], v[178:181], v[214:217], v[0:3]
	v_mfma_f32_16x16x32_bf16 v[52:55], v[174:177], v[190:193], v[52:55]
	v_mfma_f32_16x16x32_bf16 v[48:51], v[182:185], v[190:193], v[48:51]
	v_mfma_f32_16x16x32_bf16 v[36:39], v[174:177], v[198:201], v[36:39]
	v_mfma_f32_16x16x32_bf16 v[32:35], v[182:185], v[198:201], v[32:35]
	v_mfma_f32_16x16x32_bf16 v[20:23], v[174:177], v[206:209], v[20:23]
	v_mfma_f32_16x16x32_bf16 v[16:19], v[182:185], v[206:209], v[16:19]
	v_mfma_f32_16x16x32_bf16 v[4:7], v[174:177], v[218:221], v[4:7]
	v_mfma_f32_16x16x32_bf16 v[0:3], v[182:185], v[218:221], v[0:3]
	s_setprio 0
	s_barrier
	s_add_i32 s76, 0, 0x18000
	v_add_u32_e32 v136, s76, v153
	s_add_i32 s77, 0, 0x1c000
	ds_read_b128 v[146:149], v136
	ds_read_b128 v[158:161], v136 offset:1024
	ds_read_b128 v[162:165], v136 offset:2048
	ds_read_b128 v[166:169], v136 offset:3072
	v_add_u32_e32 v136, s77, v153
	ds_read_b128 v[170:173], v136
	ds_read_b128 v[174:177], v136 offset:1024
	ds_read_b128 v[178:181], v136 offset:2048
	ds_read_b128 v[182:185], v136 offset:3072
	s_add_u32 s46, s46, 0x40000
	s_addc_u32 s47, s47, 0
	s_mov_b32 m0, s57
	v_lshl_add_u64 v[226:227], s[46:47], 0, v[128:129]
	ds_read_b128 v[186:189], v157 offset:32768
	ds_read_b128 v[190:193], v157 offset:33792
	ds_read_b128 v[194:197], v157 offset:34816
	ds_read_b128 v[198:201], v157 offset:35840
	ds_read_b128 v[202:205], v157 offset:36864
	ds_read_b128 v[206:209], v157 offset:37888
	ds_read_b128 v[214:217], v157 offset:38912
	ds_read_b128 v[218:221], v157 offset:39936
	global_load_lds_dwordx4 v[226:227], off
	s_mov_b32 m0, s58
	v_lshl_add_u64 v[226:227], s[46:47], 0, v[132:133]
	global_load_lds_dwordx4 v[226:227], off
	s_waitcnt vmcnt(8) lgkmcnt(0)
	s_barrier
	s_setprio 1
	v_mfma_f32_16x16x32_bf16 v[124:127], v[146:149], v[186:189], v[124:127]
	v_mfma_f32_16x16x32_bf16 v[120:123], v[162:165], v[186:189], v[120:123]
	v_mfma_f32_16x16x32_bf16 v[108:111], v[146:149], v[194:197], v[108:111]
	v_mfma_f32_16x16x32_bf16 v[104:107], v[162:165], v[194:197], v[104:107]
	v_mfma_f32_16x16x32_bf16 v[92:95], v[146:149], v[202:205], v[92:95]
	v_mfma_f32_16x16x32_bf16 v[88:91], v[162:165], v[202:205], v[88:91]
	v_mfma_f32_16x16x32_bf16 v[76:79], v[146:149], v[214:217], v[76:79]
	v_mfma_f32_16x16x32_bf16 v[72:75], v[162:165], v[214:217], v[72:75]
	v_mfma_f32_16x16x32_bf16 v[124:127], v[158:161], v[190:193], v[124:127]
	v_mfma_f32_16x16x32_bf16 v[120:123], v[166:169], v[190:193], v[120:123]
	v_mfma_f32_16x16x32_bf16 v[108:111], v[158:161], v[198:201], v[108:111]
	v_mfma_f32_16x16x32_bf16 v[104:107], v[166:169], v[198:201], v[104:107]
	v_mfma_f32_16x16x32_bf16 v[92:95], v[158:161], v[206:209], v[92:95]
	v_mfma_f32_16x16x32_bf16 v[88:91], v[166:169], v[206:209], v[88:91]
	v_mfma_f32_16x16x32_bf16 v[76:79], v[158:161], v[218:221], v[76:79]
	v_mfma_f32_16x16x32_bf16 v[72:75], v[166:169], v[218:221], v[72:75]
	v_mfma_f32_16x16x32_bf16 v[116:119], v[170:173], v[186:189], v[116:119]
	v_mfma_f32_16x16x32_bf16 v[112:115], v[178:181], v[186:189], v[112:115]
	v_mfma_f32_16x16x32_bf16 v[100:103], v[170:173], v[194:197], v[100:103]
	v_mfma_f32_16x16x32_bf16 v[96:99], v[178:181], v[194:197], v[96:99]
	v_mfma_f32_16x16x32_bf16 v[84:87], v[170:173], v[202:205], v[84:87]
	v_mfma_f32_16x16x32_bf16 v[80:83], v[178:181], v[202:205], v[80:83]
	v_mfma_f32_16x16x32_bf16 v[68:71], v[170:173], v[214:217], v[68:71]
	v_mfma_f32_16x16x32_bf16 v[64:67], v[178:181], v[214:217], v[64:67]
	v_mfma_f32_16x16x32_bf16 v[116:119], v[174:177], v[190:193], v[116:119]
	v_mfma_f32_16x16x32_bf16 v[112:115], v[182:185], v[190:193], v[112:115]
	v_mfma_f32_16x16x32_bf16 v[100:103], v[174:177], v[198:201], v[100:103]
	v_mfma_f32_16x16x32_bf16 v[96:99], v[182:185], v[198:201], v[96:99]
	v_mfma_f32_16x16x32_bf16 v[84:87], v[174:177], v[206:209], v[84:87]
	v_mfma_f32_16x16x32_bf16 v[80:83], v[182:185], v[206:209], v[80:83]
	v_mfma_f32_16x16x32_bf16 v[68:71], v[174:177], v[218:221], v[68:71]
	v_mfma_f32_16x16x32_bf16 v[64:67], v[182:185], v[218:221], v[64:67]
	s_setprio 0
	s_barrier
; #define PG8_STAGE(bufoff, gbase, voff) do { _Pragma("unroll") for (int _i = 0; _i < 2; ++_i) \
;         __builtin_amdgcn_global_load_lds((const unsigned*)((const char*)(gbase) + (voff)[_i]), (PG8_LAS unsigned*)(lds + (bufoff) + ldsw + _i * 8192), 16, 0, 0); } while (0)
; #define PG8_LDA(dst, b, h) do { _Pragma("unroll") for (int m = 0; m < 4; ++m) _Pragma("unroll") for (int k = 0; k < 2; ++k) dst[m][k] = *(const PG8_LAS bf16x8*)(lds + PG8_SA(b, h) + aoff + m * 2048 + k * 1024); } while (0)
; #define PG8_MMA(ai, bj, At, Bt) do { __builtin_amdgcn_s_setprio(1); _Pragma("unroll") for (int m = 0; m < 4; ++m) _Pragma("unroll") for (int n = 0; n < 2; ++n) _Pragma("unroll") for (int k = 0; k < 2; ++k) \
;         acc[ai][bj][m][n] = __builtin_amdgcn_mfma_f32_16x16x32_bf16(Bt[n][k], At[m][k], acc[ai][bj][m][n], 0, 0, 0); __builtin_amdgcn_s_setprio(0); } while (0)
; #define PG8_WAIT_V(n) asm volatile("s_waitcnt vmcnt(" #n ")" ::: "memory")
; #define PG8_WAIT_L(n) asm volatile("s_waitcnt lgkmcnt(" #n ")" ::: "memory")
; #define PG8_BAR __builtin_amdgcn_s_barrier()
; #define PG8_SCHED __builtin_amdgcn_sched_barrier(0)
; template <class Epi, class Sched, bool ALIGN_EPI = false, bool SP2 = false>
; __device__ __forceinline__ void gemm_phase(PG8_LAS unsigned char* lds, const Gemm g, const Sched& S, const Epi& E, int wave_s) {
;     ...
;         for (int t = 0; t < nt; t += 2) {
;             const bool last = (t == nt - 2);
;     ...
;             PG8_LDA(At, 1, 1); PG8_STAGE(PG8_SB(1, 0), b3, voffB); PG8_STAGE(PG8_SB(1, 1), b3 + hstep, voffB); PG8_STAGE(PG8_SA(1, 0), a3, voffA);
;             PG8_WAIT_V(8); PG8_WAIT_L(0); PG8_BAR; PG8_MMA(1, 0, At, B0); PG8_MMA(1, 1, At, B1); PG8_BAR; PG8_SCHED;
;     ...
;         if constexpr (ALIGN_EPI) { if (wr == 0) PG8_BAR; }
	s_add_i32 s46, s76, s50
	v_lshl_add_u64 v[150:151], v[150:151], 0, s[12:13]
	s_mov_b32 m0, s46
	ds_read_b128 v[186:189], v157 offset:49152
	ds_read_b128 v[190:193], v157 offset:50176
	ds_read_b128 v[194:197], v157 offset:51200
	ds_read_b128 v[198:201], v157 offset:52224
	ds_read_b128 v[202:205], v157 offset:53248
	ds_read_b128 v[206:209], v157 offset:54272
	ds_read_b128 v[214:217], v157 offset:55296
	ds_read_b128 v[218:221], v157 offset:56320
	global_load_lds_dwordx4 v[150:151], off
	s_add_i32 m0, s46, 0x2000
	s_add_u32 s44, s44, 0x40080
	v_lshl_add_u64 v[150:151], v[210:211], 0, s[12:13]
	s_addc_u32 s45, s45, 0
	s_add_i32 s46, s77, s50
	global_load_lds_dwordx4 v[150:151], off
	s_mov_b32 m0, s46
	v_lshl_add_u64 v[150:151], s[44:45], 0, v[130:131]
	global_load_lds_dwordx4 v[150:151], off
	s_add_i32 m0, s46, 0x2000
	v_lshl_add_u64 v[150:151], s[44:45], 0, v[134:135]
	global_load_lds_dwordx4 v[150:151], off
	s_mov_b32 m0, s60
	v_lshl_add_u64 v[150:151], v[222:223], 0, s[12:13]
	global_load_lds_dwordx4 v[150:151], off
	s_mov_b32 m0, s61
	v_lshl_add_u64 v[150:151], v[224:225], 0, s[12:13]
	global_load_lds_dwordx4 v[150:151], off
	s_waitcnt vmcnt(8) lgkmcnt(0)
	s_barrier
	s_setprio 1
	v_mfma_f32_16x16x32_bf16 v[60:63], v[146:149], v[186:189], v[60:63]
	v_mfma_f32_16x16x32_bf16 v[56:59], v[162:165], v[186:189], v[56:59]
	v_mfma_f32_16x16x32_bf16 v[44:47], v[146:149], v[194:197], v[44:47]
	v_mfma_f32_16x16x32_bf16 v[40:43], v[162:165], v[194:197], v[40:43]
	v_mfma_f32_16x16x32_bf16 v[28:31], v[146:149], v[202:205], v[28:31]
	v_mfma_f32_16x16x32_bf16 v[24:27], v[162:165], v[202:205], v[24:27]
	v_mfma_f32_16x16x32_bf16 v[12:15], v[146:149], v[214:217], v[12:15]
	v_mfma_f32_16x16x32_bf16 v[8:11], v[162:165], v[214:217], v[8:11]
	v_mfma_f32_16x16x32_bf16 v[60:63], v[158:161], v[190:193], v[60:63]
	v_mfma_f32_16x16x32_bf16 v[56:59], v[166:169], v[190:193], v[56:59]
	v_mfma_f32_16x16x32_bf16 v[44:47], v[158:161], v[198:201], v[44:47]
	v_mfma_f32_16x16x32_bf16 v[40:43], v[166:169], v[198:201], v[40:43]
	v_mfma_f32_16x16x32_bf16 v[28:31], v[158:161], v[206:209], v[28:31]
	v_mfma_f32_16x16x32_bf16 v[24:27], v[166:169], v[206:209], v[24:27]
	v_mfma_f32_16x16x32_bf16 v[12:15], v[158:161], v[218:221], v[12:15]
	v_mfma_f32_16x16x32_bf16 v[8:11], v[166:169], v[218:221], v[8:11]
	v_mfma_f32_16x16x32_bf16 v[52:55], v[170:173], v[186:189], v[52:55]
	v_mfma_f32_16x16x32_bf16 v[48:51], v[178:181], v[186:189], v[48:51]
	v_mfma_f32_16x16x32_bf16 v[36:39], v[170:173], v[194:197], v[36:39]
	v_mfma_f32_16x16x32_bf16 v[32:35], v[178:181], v[194:197], v[32:35]
	v_mfma_f32_16x16x32_bf16 v[20:23], v[170:173], v[202:205], v[20:23]
	v_mfma_f32_16x16x32_bf16 v[16:19], v[178:181], v[202:205], v[16:19]
	v_mfma_f32_16x16x32_bf16 v[4:7], v[170:173], v[214:217], v[4:7]
	v_mfma_f32_16x16x32_bf16 v[0:3], v[178:181], v[214:217], v[0:3]
	v_mfma_f32_16x16x32_bf16 v[52:55], v[174:177], v[190:193], v[52:55]
	v_mfma_f32_16x16x32_bf16 v[48:51], v[182:185], v[190:193], v[48:51]
	v_mfma_f32_16x16x32_bf16 v[36:39], v[174:177], v[198:201], v[36:39]
	v_mfma_f32_16x16x32_bf16 v[32:35], v[182:185], v[198:201], v[32:35]
	v_mfma_f32_16x16x32_bf16 v[20:23], v[174:177], v[206:209], v[20:23]
	v_mfma_f32_16x16x32_bf16 v[16:19], v[182:185], v[206:209], v[16:19]
	v_mfma_f32_16x16x32_bf16 v[4:7], v[174:177], v[218:221], v[4:7]
	v_mfma_f32_16x16x32_bf16 v[0:3], v[182:185], v[218:221], v[0:3]
	s_setprio 0
	s_barrier
	s_add_i32 s75, s75, 2
	s_add_u32 s42, s42, 0x100
	s_addc_u32 s43, s43, 0
	s_add_u32 s73, s73, 0x100
	s_addc_u32 s74, s74, 0
	s_cmp_gt_u32 s75, 13
	s_cbranch_scc0 .LBB0_1138
	s_and_b64 vcc, exec, s[16:17]
	s_cbranch_vccz .LBB0_1141
	s_barrier

; #define PG8_STAGE(bufoff, gbase, voff) do { _Pragma("unroll") for (int _i = 0; _i < 2; ++_i) \
;         __builtin_amdgcn_global_load_lds((const unsigned*)((const char*)(gbase) + (voff)[_i]), (PG8_LAS unsigned*)(lds + (bufoff) + ldsw + _i * 8192), 16, 0, 0); } while (0)
; #define PG8_LDA(dst, b, h) do { _Pragma("unroll") for (int m = 0; m < 4; ++m) _Pragma("unroll") for (int k = 0; k < 2; ++k) dst[m][k] = *(const PG8_LAS bf16x8*)(lds + PG8_SA(b, h) + aoff + m * 2048 + k * 1024); } while (0)
; #define PG8_LDB(dst, b, h) do { _Pragma("unroll") for (int n = 0; n < 2; ++n) _Pragma("unroll") for (int k = 0; k < 2; ++k) dst[n][k] = *(const PG8_LAS bf16x8*)(lds + PG8_SB(b, h) + boff + n * 2048 + k * 1024); } while (0)
; #define PG8_MMA(ai, bj, At, Bt) do { __builtin_amdgcn_s_setprio(1); _Pragma("unroll") for (int m = 0; m < 4; ++m) _Pragma("unroll") for (int n = 0; n < 2; ++n) _Pragma("unroll") for (int k = 0; k < 2; ++k) \
;         acc[ai][bj][m][n] = __builtin_amdgcn_mfma_f32_16x16x32_bf16(Bt[n][k], At[m][k], acc[ai][bj][m][n], 0, 0, 0); __builtin_amdgcn_s_setprio(0); } while (0)
; #define PG8_WAIT_V(n) asm volatile("s_waitcnt vmcnt(" #n ")" ::: "memory")
; #define PG8_WAIT_L(n) asm volatile("s_waitcnt lgkmcnt(" #n ")" ::: "memory")
; #define PG8_BAR __builtin_amdgcn_s_barrier()
; #define PG8_SCHED __builtin_amdgcn_sched_barrier(0)
; template <class Epi, class Sched, bool ALIGN_EPI = false, bool SP2 = false>
; __device__ __forceinline__ void gemm_phase(PG8_LAS unsigned char* lds, const Gemm g, const Sched& S, const Epi& E, int wave_s) {
;     ...
;             PG8_LDB(B0, 0, 0); PG8_LDB(B1, 0, 1); PG8_SCHED; PG8_LDA(At, 0, 0); PG8_STAGE(PG8_SA(1, 1), a1 + hstep, voffA);
;             PG8_WAIT_V(8); PG8_WAIT_L(0); PG8_BAR; PG8_MMA(0, 0, At, B0); PG8_MMA(0, 1, At, B1); PG8_BAR; PG8_SCHED;
;             PG8_LDA(At, 0, 1); PG8_STAGE(PG8_SB(0, 0), b2, voffB); PG8_STAGE(PG8_SB(0, 1), b2 + hstep, voffB); PG8_STAGE(PG8_SA(0, 0), a2, voffA);
.LBB0_1257:
	ds_read_b128 v[154:157], v149
	ds_read_b128 v[158:161], v149 offset:1024
	ds_read_b128 v[162:165], v149 offset:2048
	ds_read_b128 v[166:169], v149 offset:3072
	ds_read_b128 v[170:173], v150
	ds_read_b128 v[174:177], v150 offset:1024
	ds_read_b128 v[178:181], v150 offset:2048
	ds_read_b128 v[182:185], v150 offset:3072
	s_add_u32 s38, s36, 0xfffc0080
	s_addc_u32 s39, s37, -1
	s_cmp_eq_u32 s68, 12
	s_cselect_b32 s41, s23, s39
	s_cselect_b32 s40, s64, s38
	s_cselect_b32 s39, s21, s67
	s_cselect_b32 s38, s65, s66
	v_lshl_add_u64 v[144:145], s[36:37], 0, v[136:137]
	s_add_i32 m0, s48, 0xc000
	ds_read_b128 v[186:189], v151
	ds_read_b128 v[190:193], v151 offset:1024
	ds_read_b128 v[194:197], v151 offset:2048
	ds_read_b128 v[198:201], v151 offset:3072
	ds_read_b128 v[202:205], v151 offset:4096
	ds_read_b128 v[206:209], v151 offset:5120
	ds_read_b128 v[214:217], v151 offset:6144
	ds_read_b128 v[218:221], v151 offset:7168
	global_load_lds_dwordx4 v[144:145], off
	s_add_i32 m0, s48, 0xe000
	v_lshl_add_u64 v[144:145], s[36:37], 0, v[138:139]
	global_load_lds_dwordx4 v[144:145], off
	s_waitcnt vmcnt(8) lgkmcnt(0)
	s_barrier
	s_setprio 1
	v_mfma_f32_16x16x32_bf16 v[120:123], v[154:157], v[186:189], v[120:123]
	v_mfma_f32_16x16x32_bf16 v[112:115], v[162:165], v[186:189], v[112:115]
	v_mfma_f32_16x16x32_bf16 v[104:107], v[154:157], v[194:197], v[104:107]
	v_mfma_f32_16x16x32_bf16 v[100:103], v[162:165], v[194:197], v[100:103]
	v_mfma_f32_16x16x32_bf16 v[88:91], v[154:157], v[202:205], v[88:91]
	v_mfma_f32_16x16x32_bf16 v[84:87], v[162:165], v[202:205], v[84:87]
	v_mfma_f32_16x16x32_bf16 v[76:79], v[154:157], v[214:217], v[76:79]
	v_mfma_f32_16x16x32_bf16 v[68:71], v[162:165], v[214:217], v[68:71]
	v_mfma_f32_16x16x32_bf16 v[120:123], v[158:161], v[190:193], v[120:123]
	v_mfma_f32_16x16x32_bf16 v[112:115], v[166:169], v[190:193], v[112:115]
	v_mfma_f32_16x16x32_bf16 v[104:107], v[158:161], v[198:201], v[104:107]
	v_mfma_f32_16x16x32_bf16 v[100:103], v[166:169], v[198:201], v[100:103]
	v_mfma_f32_16x16x32_bf16 v[88:91], v[158:161], v[206:209], v[88:91]
	v_mfma_f32_16x16x32_bf16 v[84:87], v[166:169], v[206:209], v[84:87]
	v_mfma_f32_16x16x32_bf16 v[76:79], v[158:161], v[218:221], v[76:79]
	v_mfma_f32_16x16x32_bf16 v[68:71], v[166:169], v[218:221], v[68:71]
	v_mfma_f32_16x16x32_bf16 v[124:127], v[170:173], v[186:189], v[124:127]
	v_mfma_f32_16x16x32_bf16 v[116:119], v[178:181], v[186:189], v[116:119]
	v_mfma_f32_16x16x32_bf16 v[108:111], v[170:173], v[194:197], v[108:111]
	v_mfma_f32_16x16x32_bf16 v[96:99], v[178:181], v[194:197], v[96:99]
	v_mfma_f32_16x16x32_bf16 v[92:95], v[170:173], v[202:205], v[92:95]
	v_mfma_f32_16x16x32_bf16 v[80:83], v[178:181], v[202:205], v[80:83]
	v_mfma_f32_16x16x32_bf16 v[72:75], v[170:173], v[214:217], v[72:75]
	v_mfma_f32_16x16x32_bf16 v[64:67], v[178:181], v[214:217], v[64:67]
	v_mfma_f32_16x16x32_bf16 v[124:127], v[174:177], v[190:193], v[124:127]
	v_mfma_f32_16x16x32_bf16 v[116:119], v[182:185], v[190:193], v[116:119]
	v_mfma_f32_16x16x32_bf16 v[108:111], v[174:177], v[198:201], v[108:111]
	v_mfma_f32_16x16x32_bf16 v[96:99], v[182:185], v[198:201], v[96:99]
	v_mfma_f32_16x16x32_bf16 v[92:95], v[174:177], v[206:209], v[92:95]
	v_mfma_f32_16x16x32_bf16 v[80:83], v[182:185], v[206:209], v[80:83]
	v_mfma_f32_16x16x32_bf16 v[72:75], v[174:177], v[218:221], v[72:75]
	v_mfma_f32_16x16x32_bf16 v[64:67], v[182:185], v[218:221], v[64:67]
	s_setprio 0
	s_barrier
	s_add_i32 s69, s60, s45
	v_lshl_add_u64 v[144:145], s[38:39], 0, v[132:133]
	s_mov_b32 m0, s69
	ds_read_b128 v[186:189], v151 offset:16384
	ds_read_b128 v[190:193], v151 offset:17408
	ds_read_b128 v[194:197], v151 offset:18432
	ds_read_b128 v[198:201], v151 offset:19456
	ds_read_b128 v[202:205], v151 offset:20480
	ds_read_b128 v[206:209], v151 offset:21504
	ds_read_b128 v[214:217], v151 offset:22528
	ds_read_b128 v[218:221], v151 offset:23552
	global_load_lds_dwordx4 v[144:145], off
	s_add_i32 m0, s69, 0x2000
	s_add_u32 s70, s38, 0x40000
	v_lshl_add_u64 v[210:211], s[38:39], 0, v[128:129]
	s_addc_u32 s71, s39, 0
	s_add_i32 s69, s61, s45
	global_load_lds_dwordx4 v[210:211], off
	v_lshl_add_u64 v[222:223], s[70:71], 0, v[132:133]
	s_mov_b32 m0, s69
	v_lshl_add_u64 v[224:225], s[40:41], 0, v[130:131]
	global_load_lds_dwordx4 v[222:223], off
	s_add_i32 m0, s69, 0x2000
	v_lshl_add_u64 v[222:223], s[70:71], 0, v[128:129]
	global_load_lds_dwordx4 v[222:223], off
	s_mov_b32 m0, s48
	v_lshl_add_u64 v[222:223], s[40:41], 0, v[134:135]
	global_load_lds_dwordx4 v[222:223], off
	s_mov_b32 m0, s49
	s_nop 0
	global_load_lds_dwordx4 v[224:225], off
	s_waitcnt vmcnt(8) lgkmcnt(0)
	s_barrier
; #define PG8_STAGE(bufoff, gbase, voff) do { _Pragma("unroll") for (int _i = 0; _i < 2; ++_i) \
;         __builtin_amdgcn_global_load_lds((const unsigned*)((const char*)(gbase) + (voff)[_i]), (PG8_LAS unsigned*)(lds + (bufoff) + ldsw + _i * 8192), 16, 0, 0); } while (0)
; #define PG8_LDA(dst, b, h) do { _Pragma("unroll") for (int m = 0; m < 4; ++m) _Pragma("unroll") for (int k = 0; k < 2; ++k) dst[m][k] = *(const PG8_LAS bf16x8*)(lds + PG8_SA(b, h) + aoff + m * 2048 + k * 1024); } while (0)
; #define PG8_LDB(dst, b, h) do { _Pragma("unroll") for (int n = 0; n < 2; ++n) _Pragma("unroll") for (int k = 0; k < 2; ++k) dst[n][k] = *(const PG8_LAS bf16x8*)(lds + PG8_SB(b, h) + boff + n * 2048 + k * 1024); } while (0)
; #define PG8_MMA(ai, bj, At, Bt) do { __builtin_amdgcn_s_setprio(1); _Pragma("unroll") for (int m = 0; m < 4; ++m) _Pragma("unroll") for (int n = 0; n < 2; ++n) _Pragma("unroll") for (int k = 0; k < 2; ++k) \
;         acc[ai][bj][m][n] = __builtin_amdgcn_mfma_f32_16x16x32_bf16(Bt[n][k], At[m][k], acc[ai][bj][m][n], 0, 0, 0); __builtin_amdgcn_s_setprio(0); } while (0)
; #define PG8_WAIT_V(n) asm volatile("s_waitcnt vmcnt(" #n ")" ::: "memory")
; #define PG8_WAIT_L(n) asm volatile("s_waitcnt lgkmcnt(" #n ")" ::: "memory")
; #define PG8_BAR __builtin_amdgcn_s_barrier()
; #define PG8_SCHED __builtin_amdgcn_sched_barrier(0)
; template <class Epi, class Sched, bool ALIGN_EPI = false, bool SP2 = false>
; __device__ __forceinline__ void gemm_phase(PG8_LAS unsigned char* lds, const Gemm g, const Sched& S, const Epi& E, int wave_s) {
;     ...
;             PG8_WAIT_V(8); PG8_WAIT_L(0); PG8_BAR; PG8_MMA(1, 0, At, B0); PG8_MMA(1, 1, At, B1); PG8_BAR; PG8_SCHED;
;             PG8_LDB(B0, 1, 0); PG8_LDB(B1, 1, 1); PG8_SCHED; PG8_LDA(At, 1, 0); PG8_STAGE(PG8_SA(0, 1), a2 + hstep, voffA);
;             PG8_WAIT_V(8); PG8_WAIT_L(0); PG8_BAR; PG8_MMA(0, 0, At, B0); PG8_MMA(0, 1, At, B1); PG8_BAR; PG8_SCHED;
	s_setprio 1
	v_mfma_f32_16x16x32_bf16 v[60:63], v[154:157], v[186:189], v[60:63]
	v_mfma_f32_16x16x32_bf16 v[56:59], v[162:165], v[186:189], v[56:59]
	v_mfma_f32_16x16x32_bf16 v[44:47], v[154:157], v[194:197], v[44:47]
	v_mfma_f32_16x16x32_bf16 v[40:43], v[162:165], v[194:197], v[40:43]
	v_mfma_f32_16x16x32_bf16 v[28:31], v[154:157], v[202:205], v[28:31]
	v_mfma_f32_16x16x32_bf16 v[24:27], v[162:165], v[202:205], v[24:27]
	v_mfma_f32_16x16x32_bf16 v[12:15], v[154:157], v[214:217], v[12:15]
	v_mfma_f32_16x16x32_bf16 v[8:11], v[162:165], v[214:217], v[8:11]
	v_mfma_f32_16x16x32_bf16 v[60:63], v[158:161], v[190:193], v[60:63]
	v_mfma_f32_16x16x32_bf16 v[56:59], v[166:169], v[190:193], v[56:59]
	v_mfma_f32_16x16x32_bf16 v[44:47], v[158:161], v[198:201], v[44:47]
	v_mfma_f32_16x16x32_bf16 v[40:43], v[166:169], v[198:201], v[40:43]
	v_mfma_f32_16x16x32_bf16 v[28:31], v[158:161], v[206:209], v[28:31]
	v_mfma_f32_16x16x32_bf16 v[24:27], v[166:169], v[206:209], v[24:27]
	v_mfma_f32_16x16x32_bf16 v[12:15], v[158:161], v[218:221], v[12:15]
	v_mfma_f32_16x16x32_bf16 v[8:11], v[166:169], v[218:221], v[8:11]
	v_mfma_f32_16x16x32_bf16 v[52:55], v[170:173], v[186:189], v[52:55]
	v_mfma_f32_16x16x32_bf16 v[48:51], v[178:181], v[186:189], v[48:51]
	v_mfma_f32_16x16x32_bf16 v[36:39], v[170:173], v[194:197], v[36:39]
	v_mfma_f32_16x16x32_bf16 v[32:35], v[178:181], v[194:197], v[32:35]
	v_mfma_f32_16x16x32_bf16 v[20:23], v[170:173], v[202:205], v[20:23]
	v_mfma_f32_16x16x32_bf16 v[16:19], v[178:181], v[202:205], v[16:19]
	v_mfma_f32_16x16x32_bf16 v[4:7], v[170:173], v[214:217], v[4:7]
	v_mfma_f32_16x16x32_bf16 v[0:3], v[178:181], v[214:217], v[0:3]
	v_mfma_f32_16x16x32_bf16 v[52:55], v[174:177], v[190:193], v[52:55]
	v_mfma_f32_16x16x32_bf16 v[48:51], v[182:185], v[190:193], v[48:51]
	v_mfma_f32_16x16x32_bf16 v[36:39], v[174:177], v[198:201], v[36:39]
	v_mfma_f32_16x16x32_bf16 v[32:35], v[182:185], v[198:201], v[32:35]
	v_mfma_f32_16x16x32_bf16 v[20:23], v[174:177], v[206:209], v[20:23]
	v_mfma_f32_16x16x32_bf16 v[16:19], v[182:185], v[206:209], v[16:19]
	v_mfma_f32_16x16x32_bf16 v[4:7], v[174:177], v[218:221], v[4:7]
	v_mfma_f32_16x16x32_bf16 v[0:3], v[182:185], v[218:221], v[0:3]
	s_setprio 0
	s_barrier
	s_add_i32 s69, 0, 0x18000
	s_add_i32 s70, 0, 0x1c000
	v_add_u32_e32 v166, s69, v147
	v_add_u32_e32 v182, s70, v147
	ds_read_b128 v[154:157], v166
	ds_read_b128 v[158:161], v166 offset:1024
	ds_read_b128 v[162:165], v166 offset:2048
	ds_read_b128 v[166:169], v166 offset:3072
	ds_read_b128 v[170:173], v182
	ds_read_b128 v[174:177], v182 offset:1024
	ds_read_b128 v[178:181], v182 offset:2048
	ds_read_b128 v[182:185], v182 offset:3072
	s_add_u32 s40, s40, 0x40000
	s_addc_u32 s41, s41, 0
	s_mov_b32 m0, s50
	v_lshl_add_u64 v[226:227], s[40:41], 0, v[134:135]
	ds_read_b128 v[186:189], v151 offset:32768
	ds_read_b128 v[190:193], v151 offset:33792
	ds_read_b128 v[194:197], v151 offset:34816
	ds_read_b128 v[198:201], v151 offset:35840
	ds_read_b128 v[202:205], v151 offset:36864
	ds_read_b128 v[206:209], v151 offset:37888
	ds_read_b128 v[214:217], v151 offset:38912
	ds_read_b128 v[218:221], v151 offset:39936
	global_load_lds_dwordx4 v[226:227], off
	s_mov_b32 m0, s51
	v_lshl_add_u64 v[226:227], s[40:41], 0, v[130:131]
	global_load_lds_dwordx4 v[226:227], off
	s_waitcnt vmcnt(8) lgkmcnt(0)
	s_barrier
	s_setprio 1
	v_mfma_f32_16x16x32_bf16 v[120:123], v[154:157], v[186:189], v[120:123]
	v_mfma_f32_16x16x32_bf16 v[112:115], v[162:165], v[186:189], v[112:115]
	v_mfma_f32_16x16x32_bf16 v[104:107], v[154:157], v[194:197], v[104:107]
	v_mfma_f32_16x16x32_bf16 v[100:103], v[162:165], v[194:197], v[100:103]
	v_mfma_f32_16x16x32_bf16 v[88:91], v[154:157], v[202:205], v[88:91]
	v_mfma_f32_16x16x32_bf16 v[84:87], v[162:165], v[202:205], v[84:87]
	v_mfma_f32_16x16x32_bf16 v[76:79], v[154:157], v[214:217], v[76:79]
	v_mfma_f32_16x16x32_bf16 v[68:71], v[162:165], v[214:217], v[68:71]
	v_mfma_f32_16x16x32_bf16 v[120:123], v[158:161], v[190:193], v[120:123]
	v_mfma_f32_16x16x32_bf16 v[112:115], v[166:169], v[190:193], v[112:115]
	v_mfma_f32_16x16x32_bf16 v[104:107], v[158:161], v[198:201], v[104:107]
	v_mfma_f32_16x16x32_bf16 v[100:103], v[166:169], v[198:201], v[100:103]
	v_mfma_f32_16x16x32_bf16 v[88:91], v[158:161], v[206:209], v[88:91]
	v_mfma_f32_16x16x32_bf16 v[84:87], v[166:169], v[206:209], v[84:87]
	v_mfma_f32_16x16x32_bf16 v[76:79], v[158:161], v[218:221], v[76:79]
	v_mfma_f32_16x16x32_bf16 v[68:71], v[166:169], v[218:221], v[68:71]
	v_mfma_f32_16x16x32_bf16 v[124:127], v[170:173], v[186:189], v[124:127]
	v_mfma_f32_16x16x32_bf16 v[116:119], v[178:181], v[186:189], v[116:119]
	v_mfma_f32_16x16x32_bf16 v[108:111], v[170:173], v[194:197], v[108:111]
	v_mfma_f32_16x16x32_bf16 v[96:99], v[178:181], v[194:197], v[96:99]
	v_mfma_f32_16x16x32_bf16 v[92:95], v[170:173], v[202:205], v[92:95]
	v_mfma_f32_16x16x32_bf16 v[80:83], v[178:181], v[202:205], v[80:83]
	v_mfma_f32_16x16x32_bf16 v[72:75], v[170:173], v[214:217], v[72:75]
	v_mfma_f32_16x16x32_bf16 v[64:67], v[178:181], v[214:217], v[64:67]
	v_mfma_f32_16x16x32_bf16 v[124:127], v[174:177], v[190:193], v[124:127]
	v_mfma_f32_16x16x32_bf16 v[116:119], v[182:185], v[190:193], v[116:119]
	v_mfma_f32_16x16x32_bf16 v[108:111], v[174:177], v[198:201], v[108:111]
	v_mfma_f32_16x16x32_bf16 v[96:99], v[182:185], v[198:201], v[96:99]
	v_mfma_f32_16x16x32_bf16 v[92:95], v[174:177], v[206:209], v[92:95]
	v_mfma_f32_16x16x32_bf16 v[80:83], v[182:185], v[206:209], v[80:83]
	v_mfma_f32_16x16x32_bf16 v[72:75], v[174:177], v[218:221], v[72:75]
	v_mfma_f32_16x16x32_bf16 v[64:67], v[182:185], v[218:221], v[64:67]
	s_setprio 0
	s_barrier
; #define PG8_STAGE(bufoff, gbase, voff) do { _Pragma("unroll") for (int _i = 0; _i < 2; ++_i) \
;         __builtin_amdgcn_global_load_lds((const unsigned*)((const char*)(gbase) + (voff)[_i]), (PG8_LAS unsigned*)(lds + (bufoff) + ldsw + _i * 8192), 16, 0, 0); } while (0)
; #define PG8_LDA(dst, b, h) do { _Pragma("unroll") for (int m = 0; m < 4; ++m) _Pragma("unroll") for (int k = 0; k < 2; ++k) dst[m][k] = *(const PG8_LAS bf16x8*)(lds + PG8_SA(b, h) + aoff + m * 2048 + k * 1024); } while (0)
; #define PG8_MMA(ai, bj, At, Bt) do { __builtin_amdgcn_s_setprio(1); _Pragma("unroll") for (int m = 0; m < 4; ++m) _Pragma("unroll") for (int n = 0; n < 2; ++n) _Pragma("unroll") for (int k = 0; k < 2; ++k) \
;         acc[ai][bj][m][n] = __builtin_amdgcn_mfma_f32_16x16x32_bf16(Bt[n][k], At[m][k], acc[ai][bj][m][n], 0, 0, 0); __builtin_amdgcn_s_setprio(0); } while (0)
; #define PG8_WAIT_V(n) asm volatile("s_waitcnt vmcnt(" #n ")" ::: "memory")
; #define PG8_WAIT_L(n) asm volatile("s_waitcnt lgkmcnt(" #n ")" ::: "memory")
; #define PG8_BAR __builtin_amdgcn_s_barrier()
; #define PG8_SCHED __builtin_amdgcn_sched_barrier(0)
; template <class Epi, class Sched, bool ALIGN_EPI = false, bool SP2 = false>
; __device__ __forceinline__ void gemm_phase(PG8_LAS unsigned char* lds, const Gemm g, const Sched& S, const Epi& E, int wave_s) {
;     ...
;         for (int t = 0; t < nt; t += 2) {
;             const bool last = (t == nt - 2);
;     ...
;             PG8_LDA(At, 1, 1); PG8_STAGE(PG8_SB(1, 0), b3, voffB); PG8_STAGE(PG8_SB(1, 1), b3 + hstep, voffB); PG8_STAGE(PG8_SA(1, 0), a3, voffA);
;             PG8_WAIT_V(8); PG8_WAIT_L(0); PG8_BAR; PG8_MMA(1, 0, At, B0); PG8_MMA(1, 1, At, B1); PG8_BAR; PG8_SCHED;
;     ...
;         if constexpr (ALIGN_EPI) { if (wr == 0) PG8_BAR; }
	s_add_i32 s40, s69, s45
	v_lshl_add_u64 v[144:145], v[144:145], 0, s[12:13]
	s_mov_b32 m0, s40
	ds_read_b128 v[186:189], v151 offset:49152
	ds_read_b128 v[190:193], v151 offset:50176
	ds_read_b128 v[194:197], v151 offset:51200
	ds_read_b128 v[198:201], v151 offset:52224
	ds_read_b128 v[202:205], v151 offset:53248
	ds_read_b128 v[206:209], v151 offset:54272
	ds_read_b128 v[214:217], v151 offset:55296
	ds_read_b128 v[218:221], v151 offset:56320
	global_load_lds_dwordx4 v[144:145], off
	s_add_i32 m0, s40, 0x2000
	s_add_u32 s38, s38, 0x40080
	v_lshl_add_u64 v[144:145], v[210:211], 0, s[12:13]
	s_addc_u32 s39, s39, 0
	s_add_i32 s40, s70, s45
	global_load_lds_dwordx4 v[144:145], off
	s_mov_b32 m0, s40
	v_lshl_add_u64 v[144:145], s[38:39], 0, v[132:133]
	global_load_lds_dwordx4 v[144:145], off
	s_add_i32 m0, s40, 0x2000
	v_lshl_add_u64 v[144:145], s[38:39], 0, v[128:129]
	global_load_lds_dwordx4 v[144:145], off
	s_mov_b32 m0, s56
	v_lshl_add_u64 v[144:145], v[222:223], 0, s[12:13]
	global_load_lds_dwordx4 v[144:145], off
	s_mov_b32 m0, s57
	v_lshl_add_u64 v[144:145], v[224:225], 0, s[12:13]
	global_load_lds_dwordx4 v[144:145], off
	s_waitcnt vmcnt(8) lgkmcnt(0)
	s_barrier
	s_setprio 1
	v_mfma_f32_16x16x32_bf16 v[60:63], v[154:157], v[186:189], v[60:63]
	v_mfma_f32_16x16x32_bf16 v[56:59], v[162:165], v[186:189], v[56:59]
	v_mfma_f32_16x16x32_bf16 v[44:47], v[154:157], v[194:197], v[44:47]
	v_mfma_f32_16x16x32_bf16 v[40:43], v[162:165], v[194:197], v[40:43]
	v_mfma_f32_16x16x32_bf16 v[28:31], v[154:157], v[202:205], v[28:31]
	v_mfma_f32_16x16x32_bf16 v[24:27], v[162:165], v[202:205], v[24:27]
	v_mfma_f32_16x16x32_bf16 v[12:15], v[154:157], v[214:217], v[12:15]
	v_mfma_f32_16x16x32_bf16 v[8:11], v[162:165], v[214:217], v[8:11]
	v_mfma_f32_16x16x32_bf16 v[60:63], v[158:161], v[190:193], v[60:63]
	v_mfma_f32_16x16x32_bf16 v[56:59], v[166:169], v[190:193], v[56:59]
	v_mfma_f32_16x16x32_bf16 v[44:47], v[158:161], v[198:201], v[44:47]
	v_mfma_f32_16x16x32_bf16 v[40:43], v[166:169], v[198:201], v[40:43]
	v_mfma_f32_16x16x32_bf16 v[28:31], v[158:161], v[206:209], v[28:31]
	v_mfma_f32_16x16x32_bf16 v[24:27], v[166:169], v[206:209], v[24:27]
	v_mfma_f32_16x16x32_bf16 v[12:15], v[158:161], v[218:221], v[12:15]
	v_mfma_f32_16x16x32_bf16 v[8:11], v[166:169], v[218:221], v[8:11]
	v_mfma_f32_16x16x32_bf16 v[52:55], v[170:173], v[186:189], v[52:55]
	v_mfma_f32_16x16x32_bf16 v[48:51], v[178:181], v[186:189], v[48:51]
	v_mfma_f32_16x16x32_bf16 v[36:39], v[170:173], v[194:197], v[36:39]
	v_mfma_f32_16x16x32_bf16 v[32:35], v[178:181], v[194:197], v[32:35]
	v_mfma_f32_16x16x32_bf16 v[20:23], v[170:173], v[202:205], v[20:23]
	v_mfma_f32_16x16x32_bf16 v[16:19], v[178:181], v[202:205], v[16:19]
	v_mfma_f32_16x16x32_bf16 v[4:7], v[170:173], v[214:217], v[4:7]
	v_mfma_f32_16x16x32_bf16 v[0:3], v[178:181], v[214:217], v[0:3]
	v_mfma_f32_16x16x32_bf16 v[52:55], v[174:177], v[190:193], v[52:55]
	v_mfma_f32_16x16x32_bf16 v[48:51], v[182:185], v[190:193], v[48:51]
	v_mfma_f32_16x16x32_bf16 v[36:39], v[174:177], v[198:201], v[36:39]
	v_mfma_f32_16x16x32_bf16 v[32:35], v[182:185], v[198:201], v[32:35]
	v_mfma_f32_16x16x32_bf16 v[20:23], v[174:177], v[206:209], v[20:23]
	v_mfma_f32_16x16x32_bf16 v[16:19], v[182:185], v[206:209], v[16:19]
	v_mfma_f32_16x16x32_bf16 v[4:7], v[174:177], v[218:221], v[4:7]
	v_mfma_f32_16x16x32_bf16 v[0:3], v[182:185], v[218:221], v[0:3]
	s_setprio 0
	s_barrier
	s_add_i32 s68, s68, 2
	s_add_u32 s36, s36, 0x100
	s_addc_u32 s37, s37, 0
	s_add_u32 s66, s66, 0x100
	s_addc_u32 s67, s67, 0
	s_cmp_gt_u32 s68, 13
	s_cbranch_scc0 .LBB0_1257
	s_and_b64 vcc, exec, s[16:17]
	s_cbranch_vccz .LBB0_1260
	s_barrier

; #define PG8_STAGE(bufoff, gbase, voff) do { _Pragma("unroll") for (int _i = 0; _i < 2; ++_i) \
;         __builtin_amdgcn_global_load_lds((const unsigned*)((const char*)(gbase) + (voff)[_i]), (PG8_LAS unsigned*)(lds + (bufoff) + ldsw + _i * 8192), 16, 0, 0); } while (0)
; #define PG8_LDA(dst, b, h) do { _Pragma("unroll") for (int m = 0; m < 4; ++m) _Pragma("unroll") for (int k = 0; k < 2; ++k) dst[m][k] = *(const PG8_LAS bf16x8*)(lds + PG8_SA(b, h) + aoff + m * 2048 + k * 1024); } while (0)
; #define PG8_LDB(dst, b, h) do { _Pragma("unroll") for (int n = 0; n < 2; ++n) _Pragma("unroll") for (int k = 0; k < 2; ++k) dst[n][k] = *(const PG8_LAS bf16x8*)(lds + PG8_SB(b, h) + boff + n * 2048 + k * 1024); } while (0)
; #define PG8_MMA(ai, bj, At, Bt) do { __builtin_amdgcn_s_setprio(1); _Pragma("unroll") for (int m = 0; m < 4; ++m) _Pragma("unroll") for (int n = 0; n < 2; ++n) _Pragma("unroll") for (int k = 0; k < 2; ++k) \
;         acc[ai][bj][m][n] = __builtin_amdgcn_mfma_f32_16x16x32_bf16(Bt[n][k], At[m][k], acc[ai][bj][m][n], 0, 0, 0); __builtin_amdgcn_s_setprio(0); } while (0)
; #define PG8_WAIT_V(n) asm volatile("s_waitcnt vmcnt(" #n ")" ::: "memory")
; #define PG8_WAIT_L(n) asm volatile("s_waitcnt lgkmcnt(" #n ")" ::: "memory")
; #define PG8_BAR __builtin_amdgcn_s_barrier()
; #define PG8_SCHED __builtin_amdgcn_sched_barrier(0)
; template <class Epi, class Sched, bool ALIGN_EPI = false, bool SP2 = false>
; __device__ __forceinline__ void gemm_phase(PG8_LAS unsigned char* lds, const Gemm g, const Sched& S, const Epi& E, int wave_s) {
;     ...
;             PG8_LDB(B0, 0, 0); PG8_LDB(B1, 0, 1); PG8_SCHED; PG8_LDA(At, 0, 0); PG8_STAGE(PG8_SA(1, 1), a1 + hstep, voffA);
;             PG8_WAIT_V(8); PG8_WAIT_L(0); PG8_BAR; PG8_MMA(0, 0, At, B0); PG8_MMA(0, 1, At, B1); PG8_BAR; PG8_SCHED;
;             PG8_LDA(At, 0, 1); PG8_STAGE(PG8_SB(0, 0), b2, voffB); PG8_STAGE(PG8_SB(0, 1), b2 + hstep, voffB); PG8_STAGE(PG8_SA(0, 0), a2, voffA);
.LBB0_1346:
	ds_read_b128 v[144:147], v151
	ds_read_b128 v[154:157], v151 offset:1024
	ds_read_b128 v[158:161], v151 offset:2048
	ds_read_b128 v[162:165], v151 offset:3072
	ds_read_b128 v[166:169], v152
	ds_read_b128 v[170:173], v152 offset:1024
	ds_read_b128 v[174:177], v152 offset:2048
	ds_read_b128 v[178:181], v152 offset:3072
	s_add_u32 s20, s18, 0x100
	s_addc_u32 s21, s19, 0
	s_cmp_eq_u32 s60, 40
	s_cselect_b32 s25, s5, s21
	s_cselect_b32 s24, s4, s20
	s_cselect_b32 s23, s17, s59
	s_cselect_b32 s22, s16, s58
	v_lshl_add_u64 v[210:211], s[18:19], 0, v[136:137]
	s_add_i32 m0, s37, 0xc000
	ds_read_b128 v[182:185], v153
	ds_read_b128 v[186:189], v153 offset:1024
	ds_read_b128 v[190:193], v153 offset:2048
	ds_read_b128 v[194:197], v153 offset:3072
	ds_read_b128 v[198:201], v153 offset:4096
	ds_read_b128 v[202:205], v153 offset:5120
	ds_read_b128 v[206:209], v153 offset:6144
	ds_read_b128 v[214:217], v153 offset:7168
	global_load_lds_dwordx4 v[210:211], off
	s_add_i32 m0, s37, 0xe000
	v_lshl_add_u64 v[210:211], s[18:19], 0, v[138:139]
	global_load_lds_dwordx4 v[210:211], off
	s_waitcnt vmcnt(8) lgkmcnt(0)
	s_barrier
	s_setprio 1
	v_mfma_f32_16x16x32_bf16 v[124:127], v[144:147], v[182:185], v[124:127]
	v_mfma_f32_16x16x32_bf16 v[120:123], v[158:161], v[182:185], v[120:123]
	v_mfma_f32_16x16x32_bf16 v[108:111], v[144:147], v[190:193], v[108:111]
	v_mfma_f32_16x16x32_bf16 v[104:107], v[158:161], v[190:193], v[104:107]
	v_mfma_f32_16x16x32_bf16 v[92:95], v[144:147], v[198:201], v[92:95]
	v_mfma_f32_16x16x32_bf16 v[88:91], v[158:161], v[198:201], v[88:91]
	v_mfma_f32_16x16x32_bf16 v[76:79], v[144:147], v[206:209], v[76:79]
	v_mfma_f32_16x16x32_bf16 v[72:75], v[158:161], v[206:209], v[72:75]
	v_mfma_f32_16x16x32_bf16 v[124:127], v[154:157], v[186:189], v[124:127]
	v_mfma_f32_16x16x32_bf16 v[120:123], v[162:165], v[186:189], v[120:123]
	v_mfma_f32_16x16x32_bf16 v[108:111], v[154:157], v[194:197], v[108:111]
	v_mfma_f32_16x16x32_bf16 v[104:107], v[162:165], v[194:197], v[104:107]
	v_mfma_f32_16x16x32_bf16 v[92:95], v[154:157], v[202:205], v[92:95]
	v_mfma_f32_16x16x32_bf16 v[88:91], v[162:165], v[202:205], v[88:91]
	v_mfma_f32_16x16x32_bf16 v[76:79], v[154:157], v[214:217], v[76:79]
	v_mfma_f32_16x16x32_bf16 v[72:75], v[162:165], v[214:217], v[72:75]
	v_mfma_f32_16x16x32_bf16 v[116:119], v[166:169], v[182:185], v[116:119]
	v_mfma_f32_16x16x32_bf16 v[112:115], v[174:177], v[182:185], v[112:115]
	v_mfma_f32_16x16x32_bf16 v[100:103], v[166:169], v[190:193], v[100:103]
	v_mfma_f32_16x16x32_bf16 v[96:99], v[174:177], v[190:193], v[96:99]
	v_mfma_f32_16x16x32_bf16 v[84:87], v[166:169], v[198:201], v[84:87]
	v_mfma_f32_16x16x32_bf16 v[80:83], v[174:177], v[198:201], v[80:83]
	v_mfma_f32_16x16x32_bf16 v[68:71], v[166:169], v[206:209], v[68:71]
	v_mfma_f32_16x16x32_bf16 v[64:67], v[174:177], v[206:209], v[64:67]
	v_mfma_f32_16x16x32_bf16 v[116:119], v[170:173], v[186:189], v[116:119]
	v_mfma_f32_16x16x32_bf16 v[112:115], v[178:181], v[186:189], v[112:115]
	v_mfma_f32_16x16x32_bf16 v[100:103], v[170:173], v[194:197], v[100:103]
	v_mfma_f32_16x16x32_bf16 v[96:99], v[178:181], v[194:197], v[96:99]
	v_mfma_f32_16x16x32_bf16 v[84:87], v[170:173], v[202:205], v[84:87]
	v_mfma_f32_16x16x32_bf16 v[80:83], v[178:181], v[202:205], v[80:83]
	v_mfma_f32_16x16x32_bf16 v[68:71], v[170:173], v[214:217], v[68:71]
	v_mfma_f32_16x16x32_bf16 v[64:67], v[178:181], v[214:217], v[64:67]
	s_setprio 0
	s_barrier
	s_add_i32 s18, s48, s36
	v_lshl_add_u64 v[210:211], s[22:23], 0, v[130:131]
	s_mov_b32 m0, s18
	ds_read_b128 v[182:185], v153 offset:16384
	ds_read_b128 v[186:189], v153 offset:17408
	ds_read_b128 v[190:193], v153 offset:18432
	ds_read_b128 v[194:197], v153 offset:19456
	ds_read_b128 v[198:201], v153 offset:20480
	ds_read_b128 v[202:205], v153 offset:21504
	ds_read_b128 v[206:209], v153 offset:22528
	ds_read_b128 v[214:217], v153 offset:23552
	global_load_lds_dwordx4 v[210:211], off
	s_add_i32 m0, s18, 0x2000
	s_add_u32 s18, s22, 0xb0000
	v_lshl_add_u64 v[218:219], s[22:23], 0, v[134:135]
	s_addc_u32 s19, s23, 0
	s_add_i32 s61, s49, s36
	global_load_lds_dwordx4 v[218:219], off
	v_lshl_add_u64 v[220:221], s[18:19], 0, v[130:131]
	s_mov_b32 m0, s61
	v_lshl_add_u64 v[222:223], s[24:25], 0, v[132:133]
	global_load_lds_dwordx4 v[220:221], off
	s_add_i32 m0, s61, 0x2000
	v_lshl_add_u64 v[220:221], s[18:19], 0, v[134:135]
	global_load_lds_dwordx4 v[220:221], off
	s_mov_b32 m0, s37
	v_lshl_add_u64 v[220:221], s[24:25], 0, v[128:129]
	global_load_lds_dwordx4 v[220:221], off
	s_mov_b32 m0, s38
	s_nop 0
	global_load_lds_dwordx4 v[222:223], off
	s_waitcnt vmcnt(8) lgkmcnt(0)
	s_barrier
; #define PG8_STAGE(bufoff, gbase, voff) do { _Pragma("unroll") for (int _i = 0; _i < 2; ++_i) \
;         __builtin_amdgcn_global_load_lds((const unsigned*)((const char*)(gbase) + (voff)[_i]), (PG8_LAS unsigned*)(lds + (bufoff) + ldsw + _i * 8192), 16, 0, 0); } while (0)
; #define PG8_LDA(dst, b, h) do { _Pragma("unroll") for (int m = 0; m < 4; ++m) _Pragma("unroll") for (int k = 0; k < 2; ++k) dst[m][k] = *(const PG8_LAS bf16x8*)(lds + PG8_SA(b, h) + aoff + m * 2048 + k * 1024); } while (0)
; #define PG8_LDB(dst, b, h) do { _Pragma("unroll") for (int n = 0; n < 2; ++n) _Pragma("unroll") for (int k = 0; k < 2; ++k) dst[n][k] = *(const PG8_LAS bf16x8*)(lds + PG8_SB(b, h) + boff + n * 2048 + k * 1024); } while (0)
; #define PG8_MMA(ai, bj, At, Bt) do { __builtin_amdgcn_s_setprio(1); _Pragma("unroll") for (int m = 0; m < 4; ++m) _Pragma("unroll") for (int n = 0; n < 2; ++n) _Pragma("unroll") for (int k = 0; k < 2; ++k) \
;         acc[ai][bj][m][n] = __builtin_amdgcn_mfma_f32_16x16x32_bf16(Bt[n][k], At[m][k], acc[ai][bj][m][n], 0, 0, 0); __builtin_amdgcn_s_setprio(0); } while (0)
; #define PG8_WAIT_V(n) asm volatile("s_waitcnt vmcnt(" #n ")" ::: "memory")
; #define PG8_WAIT_L(n) asm volatile("s_waitcnt lgkmcnt(" #n ")" ::: "memory")
; #define PG8_BAR __builtin_amdgcn_s_barrier()
; #define PG8_SCHED __builtin_amdgcn_sched_barrier(0)
; template <class Epi, class Sched, bool ALIGN_EPI = false, bool SP2 = false>
; __device__ __forceinline__ void gemm_phase(PG8_LAS unsigned char* lds, const Gemm g, const Sched& S, const Epi& E, int wave_s) {
;     ...
;             PG8_WAIT_V(8); PG8_WAIT_L(0); PG8_BAR; PG8_MMA(1, 0, At, B0); PG8_MMA(1, 1, At, B1); PG8_BAR; PG8_SCHED;
;             PG8_LDB(B0, 1, 0); PG8_LDB(B1, 1, 1); PG8_SCHED; PG8_LDA(At, 1, 0); PG8_STAGE(PG8_SA(0, 1), a2 + hstep, voffA);
;             PG8_WAIT_V(8); PG8_WAIT_L(0); PG8_BAR; PG8_MMA(0, 0, At, B0); PG8_MMA(0, 1, At, B1); PG8_BAR; PG8_SCHED;
	s_setprio 1
	v_mfma_f32_16x16x32_bf16 v[60:63], v[144:147], v[182:185], v[60:63]
	v_mfma_f32_16x16x32_bf16 v[56:59], v[158:161], v[182:185], v[56:59]
	v_mfma_f32_16x16x32_bf16 v[44:47], v[144:147], v[190:193], v[44:47]
	v_mfma_f32_16x16x32_bf16 v[40:43], v[158:161], v[190:193], v[40:43]
	v_mfma_f32_16x16x32_bf16 v[28:31], v[144:147], v[198:201], v[28:31]
	v_mfma_f32_16x16x32_bf16 v[24:27], v[158:161], v[198:201], v[24:27]
	v_mfma_f32_16x16x32_bf16 v[12:15], v[144:147], v[206:209], v[12:15]
	v_mfma_f32_16x16x32_bf16 v[8:11], v[158:161], v[206:209], v[8:11]
	v_mfma_f32_16x16x32_bf16 v[60:63], v[154:157], v[186:189], v[60:63]
	v_mfma_f32_16x16x32_bf16 v[56:59], v[162:165], v[186:189], v[56:59]
	v_mfma_f32_16x16x32_bf16 v[44:47], v[154:157], v[194:197], v[44:47]
	v_mfma_f32_16x16x32_bf16 v[40:43], v[162:165], v[194:197], v[40:43]
	v_mfma_f32_16x16x32_bf16 v[28:31], v[154:157], v[202:205], v[28:31]
	v_mfma_f32_16x16x32_bf16 v[24:27], v[162:165], v[202:205], v[24:27]
	v_mfma_f32_16x16x32_bf16 v[12:15], v[154:157], v[214:217], v[12:15]
	v_mfma_f32_16x16x32_bf16 v[8:11], v[162:165], v[214:217], v[8:11]
	v_mfma_f32_16x16x32_bf16 v[52:55], v[166:169], v[182:185], v[52:55]
	v_mfma_f32_16x16x32_bf16 v[48:51], v[174:177], v[182:185], v[48:51]
	v_mfma_f32_16x16x32_bf16 v[36:39], v[166:169], v[190:193], v[36:39]
	v_mfma_f32_16x16x32_bf16 v[32:35], v[174:177], v[190:193], v[32:35]
	v_mfma_f32_16x16x32_bf16 v[20:23], v[166:169], v[198:201], v[20:23]
	v_mfma_f32_16x16x32_bf16 v[16:19], v[174:177], v[198:201], v[16:19]
	v_mfma_f32_16x16x32_bf16 v[4:7], v[166:169], v[206:209], v[4:7]
	v_mfma_f32_16x16x32_bf16 v[0:3], v[174:177], v[206:209], v[0:3]
	v_mfma_f32_16x16x32_bf16 v[52:55], v[170:173], v[186:189], v[52:55]
	v_mfma_f32_16x16x32_bf16 v[48:51], v[178:181], v[186:189], v[48:51]
	v_mfma_f32_16x16x32_bf16 v[36:39], v[170:173], v[194:197], v[36:39]
	v_mfma_f32_16x16x32_bf16 v[32:35], v[178:181], v[194:197], v[32:35]
	v_mfma_f32_16x16x32_bf16 v[20:23], v[170:173], v[202:205], v[20:23]
	v_mfma_f32_16x16x32_bf16 v[16:19], v[178:181], v[202:205], v[16:19]
	v_mfma_f32_16x16x32_bf16 v[4:7], v[170:173], v[214:217], v[4:7]
	v_mfma_f32_16x16x32_bf16 v[0:3], v[178:181], v[214:217], v[0:3]
	s_setprio 0
	s_barrier
	s_add_i32 s61, 0, 0x18000
	s_add_i32 s62, 0, 0x1c000
	v_add_u32_e32 v162, s61, v149
	v_add_u32_e32 v178, s62, v149
	ds_read_b128 v[144:147], v162
	ds_read_b128 v[154:157], v162 offset:1024
	ds_read_b128 v[158:161], v162 offset:2048
	ds_read_b128 v[162:165], v162 offset:3072
	ds_read_b128 v[166:169], v178
	ds_read_b128 v[170:173], v178 offset:1024
	ds_read_b128 v[174:177], v178 offset:2048
	ds_read_b128 v[178:181], v178 offset:3072
	s_add_u32 s18, s24, 0xb0000
	s_addc_u32 s19, s25, 0
	s_mov_b32 m0, s39
	v_lshl_add_u64 v[224:225], s[18:19], 0, v[128:129]
	ds_read_b128 v[182:185], v153 offset:32768
	ds_read_b128 v[186:189], v153 offset:33792
	ds_read_b128 v[190:193], v153 offset:34816
	ds_read_b128 v[194:197], v153 offset:35840
	ds_read_b128 v[198:201], v153 offset:36864
	ds_read_b128 v[202:205], v153 offset:37888
	ds_read_b128 v[206:209], v153 offset:38912
	ds_read_b128 v[214:217], v153 offset:39936
	global_load_lds_dwordx4 v[224:225], off
	s_mov_b32 m0, s40
	v_lshl_add_u64 v[224:225], s[18:19], 0, v[132:133]
	global_load_lds_dwordx4 v[224:225], off
	s_waitcnt vmcnt(8) lgkmcnt(0)
	s_barrier
	s_setprio 1
	v_mfma_f32_16x16x32_bf16 v[124:127], v[144:147], v[182:185], v[124:127]
	v_mfma_f32_16x16x32_bf16 v[120:123], v[158:161], v[182:185], v[120:123]
	v_mfma_f32_16x16x32_bf16 v[108:111], v[144:147], v[190:193], v[108:111]
	v_mfma_f32_16x16x32_bf16 v[104:107], v[158:161], v[190:193], v[104:107]
	v_mfma_f32_16x16x32_bf16 v[92:95], v[144:147], v[198:201], v[92:95]
	v_mfma_f32_16x16x32_bf16 v[88:91], v[158:161], v[198:201], v[88:91]
	v_mfma_f32_16x16x32_bf16 v[76:79], v[144:147], v[206:209], v[76:79]
	v_mfma_f32_16x16x32_bf16 v[72:75], v[158:161], v[206:209], v[72:75]
	v_mfma_f32_16x16x32_bf16 v[124:127], v[154:157], v[186:189], v[124:127]
	v_mfma_f32_16x16x32_bf16 v[120:123], v[162:165], v[186:189], v[120:123]
	v_mfma_f32_16x16x32_bf16 v[108:111], v[154:157], v[194:197], v[108:111]
	v_mfma_f32_16x16x32_bf16 v[104:107], v[162:165], v[194:197], v[104:107]
	v_mfma_f32_16x16x32_bf16 v[92:95], v[154:157], v[202:205], v[92:95]
	v_mfma_f32_16x16x32_bf16 v[88:91], v[162:165], v[202:205], v[88:91]
	v_mfma_f32_16x16x32_bf16 v[76:79], v[154:157], v[214:217], v[76:79]
	v_mfma_f32_16x16x32_bf16 v[72:75], v[162:165], v[214:217], v[72:75]
	v_mfma_f32_16x16x32_bf16 v[116:119], v[166:169], v[182:185], v[116:119]
	v_mfma_f32_16x16x32_bf16 v[112:115], v[174:177], v[182:185], v[112:115]
	v_mfma_f32_16x16x32_bf16 v[100:103], v[166:169], v[190:193], v[100:103]
	v_mfma_f32_16x16x32_bf16 v[96:99], v[174:177], v[190:193], v[96:99]
	v_mfma_f32_16x16x32_bf16 v[84:87], v[166:169], v[198:201], v[84:87]
	v_mfma_f32_16x16x32_bf16 v[80:83], v[174:177], v[198:201], v[80:83]
	v_mfma_f32_16x16x32_bf16 v[68:71], v[166:169], v[206:209], v[68:71]
	v_mfma_f32_16x16x32_bf16 v[64:67], v[174:177], v[206:209], v[64:67]
	v_mfma_f32_16x16x32_bf16 v[116:119], v[170:173], v[186:189], v[116:119]
	v_mfma_f32_16x16x32_bf16 v[112:115], v[178:181], v[186:189], v[112:115]
	v_mfma_f32_16x16x32_bf16 v[100:103], v[170:173], v[194:197], v[100:103]
	v_mfma_f32_16x16x32_bf16 v[96:99], v[178:181], v[194:197], v[96:99]
	v_mfma_f32_16x16x32_bf16 v[84:87], v[170:173], v[202:205], v[84:87]
	v_mfma_f32_16x16x32_bf16 v[80:83], v[178:181], v[202:205], v[80:83]
	v_mfma_f32_16x16x32_bf16 v[68:71], v[170:173], v[214:217], v[68:71]
	v_mfma_f32_16x16x32_bf16 v[64:67], v[178:181], v[214:217], v[64:67]
	s_setprio 0
	s_barrier
; #define PG8_STAGE(bufoff, gbase, voff) do { _Pragma("unroll") for (int _i = 0; _i < 2; ++_i) \
;         __builtin_amdgcn_global_load_lds((const unsigned*)((const char*)(gbase) + (voff)[_i]), (PG8_LAS unsigned*)(lds + (bufoff) + ldsw + _i * 8192), 16, 0, 0); } while (0)
; #define PG8_LDA(dst, b, h) do { _Pragma("unroll") for (int m = 0; m < 4; ++m) _Pragma("unroll") for (int k = 0; k < 2; ++k) dst[m][k] = *(const PG8_LAS bf16x8*)(lds + PG8_SA(b, h) + aoff + m * 2048 + k * 1024); } while (0)
; #define PG8_MMA(ai, bj, At, Bt) do { __builtin_amdgcn_s_setprio(1); _Pragma("unroll") for (int m = 0; m < 4; ++m) _Pragma("unroll") for (int n = 0; n < 2; ++n) _Pragma("unroll") for (int k = 0; k < 2; ++k) \
;         acc[ai][bj][m][n] = __builtin_amdgcn_mfma_f32_16x16x32_bf16(Bt[n][k], At[m][k], acc[ai][bj][m][n], 0, 0, 0); __builtin_amdgcn_s_setprio(0); } while (0)
; #define PG8_WAIT_V(n) asm volatile("s_waitcnt vmcnt(" #n ")" ::: "memory")
; #define PG8_WAIT_L(n) asm volatile("s_waitcnt lgkmcnt(" #n ")" ::: "memory")
; #define PG8_BAR __builtin_amdgcn_s_barrier()
; #define PG8_SCHED __builtin_amdgcn_sched_barrier(0)
; template <class Epi, class Sched, bool ALIGN_EPI = false, bool SP2 = false>
; __device__ __forceinline__ void gemm_phase(PG8_LAS unsigned char* lds, const Gemm g, const Sched& S, const Epi& E, int wave_s) {
;     ...
;         for (int t = 0; t < nt; t += 2) {
;             const bool last = (t == nt - 2);
;     ...
;             PG8_LDA(At, 1, 1); PG8_STAGE(PG8_SB(1, 0), b3, voffB); PG8_STAGE(PG8_SB(1, 1), b3 + hstep, voffB); PG8_STAGE(PG8_SA(1, 0), a3, voffA);
;             PG8_WAIT_V(8); PG8_WAIT_L(0); PG8_BAR; PG8_MMA(1, 0, At, B0); PG8_MMA(1, 1, At, B1); PG8_BAR; PG8_SCHED;
;     ...
;         if constexpr (ALIGN_EPI) { if (wr == 0) PG8_BAR; }
	s_add_i32 s18, s61, s36
	v_lshl_add_u64 v[210:211], v[210:211], 0, s[10:11]
	s_mov_b32 m0, s18
	ds_read_b128 v[182:185], v153 offset:49152
	ds_read_b128 v[186:189], v153 offset:50176
	ds_read_b128 v[190:193], v153 offset:51200
	ds_read_b128 v[194:197], v153 offset:52224
	ds_read_b128 v[198:201], v153 offset:53248
	ds_read_b128 v[202:205], v153 offset:54272
	ds_read_b128 v[206:209], v153 offset:55296
	ds_read_b128 v[214:217], v153 offset:56320
	global_load_lds_dwordx4 v[210:211], off
	s_add_i32 m0, s18, 0x2000
	s_add_u32 s18, s22, 0xb0080
	v_lshl_add_u64 v[210:211], v[218:219], 0, s[10:11]
	s_addc_u32 s19, s23, 0
	s_add_i32 s22, s62, s36
	global_load_lds_dwordx4 v[210:211], off
	s_mov_b32 m0, s22
	v_lshl_add_u64 v[210:211], s[18:19], 0, v[130:131]
	global_load_lds_dwordx4 v[210:211], off
	s_add_i32 m0, s22, 0x2000
	v_lshl_add_u64 v[210:211], s[18:19], 0, v[134:135]
	global_load_lds_dwordx4 v[210:211], off
	s_mov_b32 m0, s42
	v_lshl_add_u64 v[210:211], v[220:221], 0, s[10:11]
	global_load_lds_dwordx4 v[210:211], off
	s_mov_b32 m0, s43
	v_lshl_add_u64 v[210:211], v[222:223], 0, s[10:11]
	global_load_lds_dwordx4 v[210:211], off
	s_waitcnt vmcnt(8) lgkmcnt(0)
	s_barrier
	s_setprio 1
	v_mfma_f32_16x16x32_bf16 v[60:63], v[144:147], v[182:185], v[60:63]
	v_mfma_f32_16x16x32_bf16 v[56:59], v[158:161], v[182:185], v[56:59]
	v_mfma_f32_16x16x32_bf16 v[44:47], v[144:147], v[190:193], v[44:47]
	v_mfma_f32_16x16x32_bf16 v[40:43], v[158:161], v[190:193], v[40:43]
	v_mfma_f32_16x16x32_bf16 v[28:31], v[144:147], v[198:201], v[28:31]
	v_mfma_f32_16x16x32_bf16 v[24:27], v[158:161], v[198:201], v[24:27]
	v_mfma_f32_16x16x32_bf16 v[12:15], v[144:147], v[206:209], v[12:15]
	v_mfma_f32_16x16x32_bf16 v[8:11], v[158:161], v[206:209], v[8:11]
	v_mfma_f32_16x16x32_bf16 v[60:63], v[154:157], v[186:189], v[60:63]
	v_mfma_f32_16x16x32_bf16 v[56:59], v[162:165], v[186:189], v[56:59]
	v_mfma_f32_16x16x32_bf16 v[44:47], v[154:157], v[194:197], v[44:47]
	v_mfma_f32_16x16x32_bf16 v[40:43], v[162:165], v[194:197], v[40:43]
	v_mfma_f32_16x16x32_bf16 v[28:31], v[154:157], v[202:205], v[28:31]
	v_mfma_f32_16x16x32_bf16 v[24:27], v[162:165], v[202:205], v[24:27]
	v_mfma_f32_16x16x32_bf16 v[12:15], v[154:157], v[214:217], v[12:15]
	v_mfma_f32_16x16x32_bf16 v[8:11], v[162:165], v[214:217], v[8:11]
	v_mfma_f32_16x16x32_bf16 v[52:55], v[166:169], v[182:185], v[52:55]
	v_mfma_f32_16x16x32_bf16 v[48:51], v[174:177], v[182:185], v[48:51]
	v_mfma_f32_16x16x32_bf16 v[36:39], v[166:169], v[190:193], v[36:39]
	v_mfma_f32_16x16x32_bf16 v[32:35], v[174:177], v[190:193], v[32:35]
	v_mfma_f32_16x16x32_bf16 v[20:23], v[166:169], v[198:201], v[20:23]
	v_mfma_f32_16x16x32_bf16 v[16:19], v[174:177], v[198:201], v[16:19]
	v_mfma_f32_16x16x32_bf16 v[4:7], v[166:169], v[206:209], v[4:7]
	v_mfma_f32_16x16x32_bf16 v[0:3], v[174:177], v[206:209], v[0:3]
	v_mfma_f32_16x16x32_bf16 v[52:55], v[170:173], v[186:189], v[52:55]
	v_mfma_f32_16x16x32_bf16 v[48:51], v[178:181], v[186:189], v[48:51]
	v_mfma_f32_16x16x32_bf16 v[36:39], v[170:173], v[194:197], v[36:39]
	v_mfma_f32_16x16x32_bf16 v[32:35], v[178:181], v[194:197], v[32:35]
	v_mfma_f32_16x16x32_bf16 v[20:23], v[170:173], v[202:205], v[20:23]
	v_mfma_f32_16x16x32_bf16 v[16:19], v[178:181], v[202:205], v[16:19]
	v_mfma_f32_16x16x32_bf16 v[4:7], v[170:173], v[214:217], v[4:7]
	v_mfma_f32_16x16x32_bf16 v[0:3], v[178:181], v[214:217], v[0:3]
	s_setprio 0
	s_barrier
	s_add_i32 s60, s60, 2
	s_add_u32 s58, s58, 0x100
	s_addc_u32 s59, s59, 0
	s_cmp_gt_u32 s60, 41
	s_mov_b64 s[18:19], s[20:21]
	s_cbranch_scc0 .LBB0_1346
	s_and_b64 vcc, exec, s[12:13]
	s_cbranch_vccz .LBB0_1349
	s_barrier
